# attention: K/V tile halves kept in a 4-slot LDS ring (continuing tiles load only the new half); branch-0 blocks skip the previous-branch row loads
# speedup vs baseline: 1.0208x; 1.0208x over previous
.LBB0_174:
	v_writelane_b32 v248, s10, 5
	v_writelane_b32 v248, s16, 3
	s_nop 1
	v_writelane_b32 v248, s17, 4
	s_or_b64 exec, exec, s[4:5]
	v_readlane_b32 s4, v249, 15
	v_readlane_b32 s5, v249, 16
	s_andn2_b64 vcc, exec, s[4:5]
	s_cbranch_vccnz .LBB0_203
	s_waitcnt lgkmcnt(0)
	s_barrier
	v_readfirstlane_b32 s67, v158
	s_lshr_b32 s67, s67, 6
	s_lshr_b32 s68, s67, 2
	v_and_b32_e32 v0, 63, v158
	v_and_b32_e32 v1, 15, v0
	v_lshrrev_b32_e32 v2, 4, v0
	s_lshl_b32 s4, s67, 4
	v_add_u32_e32 v17, s4, v1
	v_and_b32_e32 v37, 6, v1
	v_xor_b32_e32 v37, v2, v37
	v_lshlrev_b32_e32 v37, 4, v37
	v_lshl_add_u32 v4, v1, 7, v37
	v_xor_b32_e32 v5, 64, v4
	v_lshrrev_b32_e32 v38, 2, v1
	v_lshl_add_u32 v38, v2, 2, v38
	v_add_u32_e32 v39, s4, v38
	v_and_b32_e32 v40, 6, v38
	v_and_b32_e32 v41, 3, v1
	v_lshrrev_b32_e32 v42, 1, v41
	v_and_b32_e32 v43, 1, v1
	v_lshlrev_b32_e32 v43, 3, v43
	v_add_u32_e32 v45, 0x90, v39
	v_and_b32_e32 v45, 0xff, v45
	v_or_b32_e32 v44, 0, v42
	v_xor_b32_e32 v44, v44, v40
	v_lshlrev_b32_e32 v44, 4, v44
	v_add_u32_e32 v44, v44, v43
	v_lshl_add_u32 v46, v38, 7, v44
	v_add_u32_e32 v6, 0x10000, v46
	v_or_b32_e32 v44, 2, v42
	v_xor_b32_e32 v44, v44, v40
	v_lshlrev_b32_e32 v44, 4, v44
	v_add_u32_e32 v44, v44, v43
	v_lshl_add_u32 v46, v38, 7, v44
	v_add_u32_e32 v7, 0x10000, v46
	v_or_b32_e32 v44, 4, v42
	v_xor_b32_e32 v44, v44, v40
	v_lshlrev_b32_e32 v44, 4, v44
	v_add_u32_e32 v44, v44, v43
	v_lshl_add_u32 v46, v38, 7, v44
	v_add_u32_e32 v8, 0x10000, v46
	v_or_b32_e32 v44, 6, v42
	v_xor_b32_e32 v44, v44, v40
	v_lshlrev_b32_e32 v44, 4, v44
	v_add_u32_e32 v44, v44, v43
	v_lshl_add_u32 v46, v38, 7, v44
	v_add_u32_e32 v9, 0x10000, v46
	v_lshrrev_b32_e32 v14, 3, v158
	v_and_b32_e32 v44, 7, v0
	v_lshrrev_b32_e32 v45, 3, v0
	v_and_b32_e32 v45, 6, v45
	v_xor_b32_e32 v44, v44, v45
	v_lshlrev_b32_e32 v15, 4, v44
	v_lshlrev_b32_e32 v44, 2, v2
	v_sub_u32_e32 v45, v1, v44
	v_add_u32_e32 v45, 0x80, v45
	v_cvt_f32_i32_e32 v16, v45
	v_lshlrev_b32_e32 v18, 4, v2
	v_lshlrev_b32_e32 v19, 3, v2
	v_or_b32_e32 v45, 0, v44
	v_cmp_lt_u32_e64 s[54:55], v45, v1
	v_cmp_gt_u32_e64 s[70:71], v45, v1
	v_or_b32_e32 v45, 1, v44
	v_cmp_lt_u32_e64 s[56:57], v45, v1
	v_cmp_gt_u32_e64 s[72:73], v45, v1
	v_or_b32_e32 v45, 2, v44
	v_cmp_lt_u32_e64 s[58:59], v45, v1
	v_cmp_gt_u32_e64 s[74:75], v45, v1
	v_or_b32_e32 v45, 3, v44
	v_cmp_lt_u32_e64 s[60:61], v45, v1
	v_cmp_gt_u32_e64 s[76:77], v45, v1
	v_mov_b32_e32 v190, 0
	v_mov_b32_e32 v191, 0
	s_mov_b32 s63, s2

.Latt_roles_1:
	s_add_i32 s4, s65, 1
	v_cvt_f32_ubyte0_e32 v0, s4
	v_mul_f32_e32 v0, -0.5, v0
	v_exp_f32_e32 v0, v0
	s_nop 1
	v_mul_f32_e32 v20, 0x3fb8aa3b, v0
	s_mov_b32 s4, 0
	s_lshr_b32 s11, s4, 4
	s_and_b32 s12, s4, 15
	s_lshl_b32 s28, s11, 1
	s_lshl_b32 s13, s64, 4
	s_add_i32 s13, s13, s12
	s_lshr_b32 s14, s12, 2
	s_and_b32 s15, s12, 3
	s_lshl_b32 s16, s64, 2
	s_add_i32 s15, s16, s15
	s_cmp_eq_u32 s11, 1
	s_cselect_b32 s29, s14, 0
	s_cselect_b32 s30, s15, s13
	s_cmp_eq_u32 s11, 2
	s_cselect_b32 s29, s12, s29
	s_cselect_b32 s30, s64, s30
	s_mov_b32 s88, 0
	s_mov_b32 s89, 0
	s_lshl_b32 s5, s88, 7
	s_lshl_b32 s6, s67, 3
	s_add_i32 s5, s5, s6
	s_add_i32 s6, s30, -1
	s_lshl_b32 s6, s6, 7
	s_cmp_eq_u32 s89, 1
	s_cbranch_scc1 .Latt_half_2
	s_add_i32 s7, s5, 0
	s_and_b32 s7, s7, 511
	s_lshl_b32 s7, s7, 7
	s_add_i32 m0, s7, s4
	s_add_i32 s7, s6, 0
	v_add_u32_e32 v0, s7, v14
	v_lshlrev_b32_e32 v0, s28, v0
	v_add_u32_e32 v0, s29, v0
	v_max_i32_e32 v0, 0, v0
	v_lshl_or_b32 v2, v0, 7, v15
	v_lshl_add_u64 v[38:39], s[36:37], 0, v[2:3]
	global_load_lds_dwordx4 v[38:39], off
	s_add_i32 s7, s5, 64
	s_and_b32 s7, s7, 511
	s_lshl_b32 s7, s7, 7
	s_add_i32 m0, s7, s4
	s_add_i32 s7, s6, 64
	v_add_u32_e32 v0, s7, v14
	v_lshlrev_b32_e32 v0, s28, v0
	v_add_u32_e32 v0, s29, v0
	v_max_i32_e32 v0, 0, v0
	v_lshl_or_b32 v2, v0, 7, v15
	v_lshl_add_u64 v[40:41], s[36:37], 0, v[2:3]
	global_load_lds_dwordx4 v[40:41], off
.Latt_half_2:
	s_add_i32 s7, s5, 128
	s_and_b32 s7, s7, 511
	s_lshl_b32 s7, s7, 7
	s_add_i32 m0, s7, s4
	s_add_i32 s7, s6, 128
	v_add_u32_e32 v0, s7, v14
	v_lshlrev_b32_e32 v0, s28, v0
	v_add_u32_e32 v0, s29, v0
	v_max_i32_e32 v0, 0, v0
	v_lshl_or_b32 v2, v0, 7, v15
	v_lshl_add_u64 v[42:43], s[36:37], 0, v[2:3]
	global_load_lds_dwordx4 v[42:43], off
	s_add_i32 s7, s5, 192
	s_and_b32 s7, s7, 511
	s_lshl_b32 s7, s7, 7
	s_add_i32 m0, s7, s4
	s_add_i32 s7, s6, 192
	v_add_u32_e32 v0, s7, v14
	v_lshlrev_b32_e32 v0, s28, v0
	v_add_u32_e32 v0, s29, v0
	v_max_i32_e32 v0, 0, v0
	v_lshl_or_b32 v2, v0, 7, v15
	v_lshl_add_u64 v[44:45], s[36:37], 0, v[2:3]
	global_load_lds_dwordx4 v[44:45], off
	s_mov_b32 s9, 0x10000
	s_lshl_b32 s5, s88, 7
	s_lshl_b32 s6, s67, 3
	s_add_i32 s5, s5, s6
	s_add_i32 s6, s30, -1
	s_lshl_b32 s6, s6, 7
	s_cmp_eq_u32 s89, 1
	s_cbranch_scc1 .Latt_half_3
	s_add_i32 s7, s5, 0
	s_and_b32 s7, s7, 511
	s_lshl_b32 s7, s7, 7
	s_add_i32 m0, s7, s9
	s_add_i32 s7, s6, 0
	v_add_u32_e32 v0, s7, v14
	v_lshlrev_b32_e32 v0, s28, v0
	v_add_u32_e32 v0, s29, v0
	v_max_i32_e32 v0, 0, v0
	v_lshl_or_b32 v2, v0, 7, v15
	v_lshl_add_u64 v[38:39], s[38:39], 0, v[2:3]
	global_load_lds_dwordx4 v[38:39], off
	s_add_i32 s7, s5, 64
	s_and_b32 s7, s7, 511
	s_lshl_b32 s7, s7, 7
	s_add_i32 m0, s7, s9
	s_add_i32 s7, s6, 64
	v_add_u32_e32 v0, s7, v14
	v_lshlrev_b32_e32 v0, s28, v0
	v_add_u32_e32 v0, s29, v0
	v_max_i32_e32 v0, 0, v0
	v_lshl_or_b32 v2, v0, 7, v15
	v_lshl_add_u64 v[40:41], s[38:39], 0, v[2:3]
	global_load_lds_dwordx4 v[40:41], off
.Latt_half_3:
	s_add_i32 s7, s5, 128
	s_and_b32 s7, s7, 511
	s_lshl_b32 s7, s7, 7
	s_add_i32 m0, s7, s9
	s_add_i32 s7, s6, 128
	v_add_u32_e32 v0, s7, v14
	v_lshlrev_b32_e32 v0, s28, v0
	v_add_u32_e32 v0, s29, v0
	v_max_i32_e32 v0, 0, v0
	v_lshl_or_b32 v2, v0, 7, v15
	v_lshl_add_u64 v[42:43], s[38:39], 0, v[2:3]
	global_load_lds_dwordx4 v[42:43], off
	s_add_i32 s7, s5, 192
	s_and_b32 s7, s7, 511
	s_lshl_b32 s7, s7, 7
	s_add_i32 m0, s7, s9
	s_add_i32 s7, s6, 192
	v_add_u32_e32 v0, s7, v14
	v_lshlrev_b32_e32 v0, s28, v0
	v_add_u32_e32 v0, s29, v0
	v_max_i32_e32 v0, 0, v0
	v_lshl_or_b32 v2, v0, 7, v15
	v_lshl_add_u64 v[44:45], s[38:39], 0, v[2:3]
	global_load_lds_dwordx4 v[44:45], off
	s_lshl_b32 s5, s30, 7
	v_add_u32_e32 v82, s5, v17
	v_lshlrev_b32_e32 v82, s28, v82
	v_add_u32_e32 v82, s29, v82
	v_lshl_add_u32 v1, v82, 11, v18
	global_load_dwordx4 v[48:51], v1, s[40:41]
	global_load_dwordx4 v[52:55], v1, s[40:41] offset:64
	s_cmp_lt_u32 s4, 16
	s_cbranch_scc1 .Latt_odummy_4
	v_lshl_add_u32 v1, v82, 11, v19
	global_load_dwordx2 v[64:65], v1, s[42:43] offset:0
	global_load_dwordx2 v[66:67], v1, s[42:43] offset:32
	global_load_dwordx2 v[68:69], v1, s[42:43] offset:64
	global_load_dwordx2 v[70:71], v1, s[42:43] offset:96
	v_lshlrev_b32_e32 v0, 2, v82
	global_load_dword v80, v0, s[44:45]
	s_branch .Latt_odone_5
.Latt_odummy_4:
	global_load_dword v64, v3, s[44:45]
	global_load_dword v66, v3, s[44:45]
	global_load_dword v68, v3, s[44:45]
	global_load_dword v70, v3, s[44:45]
	global_load_dword v80, v3, s[44:45]
.Latt_odone_5:
	s_mov_b32 s4, 1
	s_lshr_b32 s11, s4, 4
	s_and_b32 s12, s4, 15
	s_lshl_b32 s28, s11, 1
	s_lshl_b32 s13, s64, 4
	s_add_i32 s13, s13, s12
	s_lshr_b32 s14, s12, 2
	s_and_b32 s15, s12, 3
	s_lshl_b32 s16, s64, 2
	s_add_i32 s15, s16, s15
	s_cmp_eq_u32 s11, 1
	s_cselect_b32 s29, s14, 0
	s_cselect_b32 s30, s15, s13
	s_cmp_eq_u32 s11, 2
	s_cselect_b32 s29, s12, s29
	s_cselect_b32 s30, s64, s30
	s_lshl_b32 s5, s30, 7
	v_add_u32_e32 v82, s5, v17
	v_lshlrev_b32_e32 v82, s28, v82
	v_add_u32_e32 v82, s29, v82
	v_lshl_add_u32 v1, v82, 11, v18
	global_load_dwordx4 v[56:59], v1, s[40:41]
	global_load_dwordx4 v[60:63], v1, s[40:41] offset:64
	s_cmp_lt_u32 s4, 16
	s_cbranch_scc1 .Latt_odummy_6
	v_lshl_add_u32 v1, v82, 11, v19
	global_load_dwordx2 v[72:73], v1, s[42:43] offset:0
	global_load_dwordx2 v[74:75], v1, s[42:43] offset:32
	global_load_dwordx2 v[76:77], v1, s[42:43] offset:64
	global_load_dwordx2 v[78:79], v1, s[42:43] offset:96
	v_lshlrev_b32_e32 v0, 2, v82
	global_load_dword v81, v0, s[44:45]
	s_branch .Latt_odone_7
.Latt_odummy_6:
	global_load_dword v72, v3, s[44:45]
	global_load_dword v74, v3, s[44:45]
	global_load_dword v76, v3, s[44:45]
	global_load_dword v78, v3, s[44:45]
	global_load_dword v81, v3, s[44:45]
.Latt_odone_7:
	s_waitcnt vmcnt(0)
	s_barrier
	s_cmp_eq_u32 s68, 0
	s_cbranch_scc1 .Latt_lead_8
	s_mov_b32 s4, 1
	s_lshr_b32 s11, s4, 4
	s_and_b32 s12, s4, 15
	s_lshl_b32 s28, s11, 1
	s_lshl_b32 s13, s64, 4
	s_add_i32 s13, s13, s12
	s_lshr_b32 s14, s12, 2
	s_and_b32 s15, s12, 3
	s_lshl_b32 s16, s64, 2
	s_add_i32 s15, s16, s15
	s_cmp_eq_u32 s11, 1
	s_cselect_b32 s29, s14, 0
	s_cselect_b32 s30, s15, s13
	s_cmp_eq_u32 s11, 2
	s_cselect_b32 s29, s12, s29
	s_cselect_b32 s30, s64, s30
	s_lshr_b32 s11, s4, 4
	s_and_b32 s12, s4, 15
	s_and_b32 s13, s12, 3
	s_cmp_lg_u32 s12, 0
	s_cselect_b32 s14, 1, 0
	s_lshr_b32 s15, s12, 2
	s_and_b32 s16, s12, 3
	s_add_i32 s15, s15, s16
	s_add_i32 s15, s15, 1
	s_and_b32 s15, s15, 3
	s_cmp_lg_u32 s16, 0
	s_cselect_b32 s16, 1, 0
	s_cmp_eq_u32 s11, 1
	s_cselect_b32 s13, s15, s13
	s_cselect_b32 s14, s16, s14
	s_and_b32 s15, s12, 1
	s_lshl_b32 s15, s15, 1
	s_add_i32 s15, s15, 1
	s_cmp_eq_u32 s11, 2
	s_cselect_b32 s88, s15, s13
	s_cselect_b32 s89, 0, s14
	s_lshl_b32 s5, s88, 7
	s_lshl_b32 s6, s67, 3
	s_add_i32 s5, s5, s6
	s_add_i32 s6, s30, -1
	s_lshl_b32 s6, s6, 7
	s_cmp_eq_u32 s89, 1
	s_cbranch_scc1 .Latt_half_9
	s_add_i32 s7, s5, 0
	s_and_b32 s7, s7, 511
	s_lshl_b32 s7, s7, 7
	s_add_i32 m0, s7, s49
	s_add_i32 s7, s6, 0
	v_add_u32_e32 v0, s7, v14
	v_lshlrev_b32_e32 v0, s28, v0
	v_add_u32_e32 v0, s29, v0
	v_max_i32_e32 v0, 0, v0
	v_lshl_or_b32 v2, v0, 7, v15
	v_lshl_add_u64 v[38:39], s[50:51], 0, v[2:3]
	global_load_lds_dwordx4 v[38:39], off
	s_add_i32 s7, s5, 64
	s_and_b32 s7, s7, 511
	s_lshl_b32 s7, s7, 7
	s_add_i32 m0, s7, s49
	s_add_i32 s7, s6, 64
	v_add_u32_e32 v0, s7, v14
	v_lshlrev_b32_e32 v0, s28, v0
	v_add_u32_e32 v0, s29, v0
	v_max_i32_e32 v0, 0, v0
	v_lshl_or_b32 v2, v0, 7, v15
	v_lshl_add_u64 v[40:41], s[50:51], 0, v[2:3]
	global_load_lds_dwordx4 v[40:41], off
.Latt_half_9:
	s_add_i32 s7, s5, 128
	s_and_b32 s7, s7, 511
	s_lshl_b32 s7, s7, 7
	s_add_i32 m0, s7, s49
	s_add_i32 s7, s6, 128
	v_add_u32_e32 v0, s7, v14
	v_lshlrev_b32_e32 v0, s28, v0
	v_add_u32_e32 v0, s29, v0
	v_max_i32_e32 v0, 0, v0
	v_lshl_or_b32 v2, v0, 7, v15
	v_lshl_add_u64 v[42:43], s[50:51], 0, v[2:3]
	global_load_lds_dwordx4 v[42:43], off
	s_add_i32 s7, s5, 192
	s_and_b32 s7, s7, 511
	s_lshl_b32 s7, s7, 7
	s_add_i32 m0, s7, s49
	s_add_i32 s7, s6, 192
	v_add_u32_e32 v0, s7, v14
	v_lshlrev_b32_e32 v0, s28, v0
	v_add_u32_e32 v0, s29, v0
	v_max_i32_e32 v0, 0, v0
	v_lshl_or_b32 v2, v0, 7, v15
	v_lshl_add_u64 v[44:45], s[50:51], 0, v[2:3]
	global_load_lds_dwordx4 v[44:45], off
	s_waitcnt vmcnt(0)
	s_barrier

.Latt_blk:
	s_lshr_b32 s11, s53, 4
	s_and_b32 s12, s53, 15
	s_lshl_b32 s20, s11, 1
	s_lshl_b32 s13, s64, 4
	s_add_i32 s13, s13, s12
	s_lshr_b32 s14, s12, 2
	s_and_b32 s15, s12, 3
	s_lshl_b32 s16, s64, 2
	s_add_i32 s15, s16, s15
	s_cmp_eq_u32 s11, 1
	s_cselect_b32 s21, s14, 0
	s_cselect_b32 s24, s15, s13
	s_cmp_eq_u32 s11, 2
	s_cselect_b32 s21, s12, s21
	s_cselect_b32 s24, s64, s24
	s_add_i32 s4, s53, 1
	s_min_u32 s4, s4, 47
	s_lshr_b32 s11, s4, 4
	s_and_b32 s12, s4, 15
	s_lshl_b32 s28, s11, 1
	s_lshl_b32 s13, s64, 4
	s_add_i32 s13, s13, s12
	s_lshr_b32 s14, s12, 2
	s_and_b32 s15, s12, 3
	s_lshl_b32 s16, s64, 2
	s_add_i32 s15, s16, s15
	s_cmp_eq_u32 s11, 1
	s_cselect_b32 s29, s14, 0
	s_cselect_b32 s30, s15, s13
	s_cmp_eq_u32 s11, 2
	s_cselect_b32 s29, s12, s29
	s_cselect_b32 s30, s64, s30
	s_lshr_b32 s11, s4, 4
	s_and_b32 s12, s4, 15
	s_and_b32 s13, s12, 3
	s_cmp_lg_u32 s12, 0
	s_cselect_b32 s14, 1, 0
	s_lshr_b32 s15, s12, 2
	s_and_b32 s16, s12, 3
	s_add_i32 s15, s15, s16
	s_add_i32 s15, s15, 1
	s_and_b32 s15, s15, 3
	s_cmp_lg_u32 s16, 0
	s_cselect_b32 s16, 1, 0
	s_cmp_eq_u32 s11, 1
	s_cselect_b32 s13, s15, s13
	s_cselect_b32 s14, s16, s14
	s_and_b32 s15, s12, 1
	s_lshl_b32 s15, s15, 1
	s_add_i32 s15, s15, 1
	s_cmp_eq_u32 s11, 2
	s_cselect_b32 s88, s15, s13
	s_cselect_b32 s89, 0, s14
	s_lshl_b32 s5, s88, 7
	s_lshl_b32 s6, s67, 3
	s_add_i32 s5, s5, s6
	s_add_i32 s6, s30, -1
	s_lshl_b32 s6, s6, 7
	s_cmp_eq_u32 s89, 1
	s_cbranch_scc1 .Latt_half_10
	s_add_i32 s7, s5, 0
	s_and_b32 s7, s7, 511
	s_lshl_b32 s7, s7, 7
	s_add_i32 m0, s7, s48
	s_add_i32 s7, s6, 0
	v_add_u32_e32 v0, s7, v14
	v_lshlrev_b32_e32 v0, s28, v0
	v_add_u32_e32 v0, s29, v0
	v_max_i32_e32 v0, 0, v0
	v_lshl_or_b32 v2, v0, 7, v15
	v_lshl_add_u64 v[38:39], s[46:47], 0, v[2:3]
	global_load_lds_dwordx4 v[38:39], off
	s_add_i32 s7, s5, 64
	s_and_b32 s7, s7, 511
	s_lshl_b32 s7, s7, 7
	s_add_i32 m0, s7, s48
	s_add_i32 s7, s6, 64
	v_add_u32_e32 v0, s7, v14
	v_lshlrev_b32_e32 v0, s28, v0
	v_add_u32_e32 v0, s29, v0
	v_max_i32_e32 v0, 0, v0
	v_lshl_or_b32 v2, v0, 7, v15
	v_lshl_add_u64 v[40:41], s[46:47], 0, v[2:3]
	global_load_lds_dwordx4 v[40:41], off
.Latt_half_10:
	s_add_i32 s7, s5, 128
	s_and_b32 s7, s7, 511
	s_lshl_b32 s7, s7, 7
	s_add_i32 m0, s7, s48
	s_add_i32 s7, s6, 128
	v_add_u32_e32 v0, s7, v14
	v_lshlrev_b32_e32 v0, s28, v0
	v_add_u32_e32 v0, s29, v0
	v_max_i32_e32 v0, 0, v0
	v_lshl_or_b32 v2, v0, 7, v15
	v_lshl_add_u64 v[42:43], s[46:47], 0, v[2:3]
	global_load_lds_dwordx4 v[42:43], off
	s_add_i32 s7, s5, 192
	s_and_b32 s7, s7, 511
	s_lshl_b32 s7, s7, 7
	s_add_i32 m0, s7, s48
	s_add_i32 s7, s6, 192
	v_add_u32_e32 v0, s7, v14
	v_lshlrev_b32_e32 v0, s28, v0
	v_add_u32_e32 v0, s29, v0
	v_max_i32_e32 v0, 0, v0
	v_lshl_or_b32 v2, v0, 7, v15
	v_lshl_add_u64 v[44:45], s[46:47], 0, v[2:3]
	global_load_lds_dwordx4 v[44:45], off
	s_lshr_b32 s11, s53, 4
	s_and_b32 s12, s53, 15
	s_and_b32 s13, s12, 3
	s_cmp_lg_u32 s12, 0
	s_cselect_b32 s14, 1, 0
	s_lshr_b32 s15, s12, 2
	s_and_b32 s16, s12, 3
	s_add_i32 s15, s15, s16
	s_add_i32 s15, s15, 1
	s_and_b32 s15, s15, 3
	s_cmp_lg_u32 s16, 0
	s_cselect_b32 s16, 1, 0
	s_cmp_eq_u32 s11, 1
	s_cselect_b32 s13, s15, s13
	s_cselect_b32 s14, s16, s14
	s_and_b32 s15, s12, 1
	s_lshl_b32 s15, s15, 1
	s_add_i32 s15, s15, 1
	s_cmp_eq_u32 s11, 2
	s_cselect_b32 s90, s15, s13
	s_cselect_b32 s31, 0, s14
	s_lshl_b32 s91, s90, 3
	s_add_i32 s91, s91, s67
	s_add_i32 s5, s91, 0
	s_and_b32 s5, s5, 31
	s_lshl_b32 s5, s5, 11
	v_add_u32_e32 v0, s5, v4
	v_add_u32_e32 v1, s5, v5
	ds_read_b128 v[84:87], v0
	ds_read_b128 v[88:91], v1
	s_add_i32 s5, s91, 1
	s_and_b32 s5, s5, 31
	s_lshl_b32 s5, s5, 11
	v_add_u32_e32 v0, s5, v4
	v_add_u32_e32 v1, s5, v5
	ds_read_b128 v[92:95], v0
	ds_read_b128 v[96:99], v1
	s_add_i32 s5, s91, 2
	s_and_b32 s5, s5, 31
	s_lshl_b32 s5, s5, 11
	v_add_u32_e32 v0, s5, v4
	v_add_u32_e32 v1, s5, v5
	ds_read_b128 v[100:103], v0
	ds_read_b128 v[104:107], v1
	s_add_i32 s5, s91, 3
	s_and_b32 s5, s5, 31
	s_lshl_b32 s5, s5, 11
	v_add_u32_e32 v0, s5, v4
	v_add_u32_e32 v1, s5, v5
	ds_read_b128 v[108:111], v0
	ds_read_b128 v[112:115], v1
	s_add_i32 s5, s91, 4
	s_and_b32 s5, s5, 31
	s_lshl_b32 s5, s5, 11
	v_add_u32_e32 v0, s5, v4
	v_add_u32_e32 v1, s5, v5
	ds_read_b128 v[116:119], v0
	ds_read_b128 v[120:123], v1
	s_add_i32 s5, s91, 5
	s_and_b32 s5, s5, 31
	s_lshl_b32 s5, s5, 11
	v_add_u32_e32 v0, s5, v4
	v_add_u32_e32 v1, s5, v5
	ds_read_b128 v[124:127], v0
	ds_read_b128 v[128:131], v1
	s_lshl_b32 s5, 1, s20
	v_cvt_f32_u32_e32 v0, s5
	v_mul_f32_e32 v21, v20, v0
	v_xor_b32_e32 v0, 0x80000000, v21
	v_mul_f32_e32 v22, v16, v0
	v_add_f32_e32 v23, v21, v22
	v_add_f32_e32 v1, v21, v21
	v_add_f32_e32 v24, v1, v22
	v_fma_f32 v25, v21, v192, v22
	v_mul_f32_e32 v26, 0, v21
	v_mul_f32_e32 v27, 0x41800000, v21
	v_mul_f32_e32 v28, 0x42000000, v21
	v_mul_f32_e32 v29, 0x42400000, v21
	v_mul_f32_e32 v30, 0x42800000, v21
	v_mul_f32_e32 v31, 0x42a00000, v21
	v_mul_f32_e32 v32, 0x42c00000, v21
	v_mul_f32_e32 v33, 0x42e00000, v21
	v_mul_f32_e32 v34, 0x43000000, v21
	s_cmp_eq_u32 s24, 0
	s_cbranch_scc0 .Latt_n0skip_11
	s_cmp_lt_u32 s67, 1
	s_cbranch_scc0 .Latt_n0t_12
	v_mov_b32_e32 v33, v223

.Latt_n0t_19:
.Latt_n0skip_11:
	s_waitcnt lgkmcnt(10)
	v_mfma_f32_16x16x32_bf16 v[132:135], v[84:87], v[48:51], v[22:25]
	v_mfma_f32_16x16x32_bf16 v[132:135], v[88:91], v[52:55], v[132:135]
	s_waitcnt lgkmcnt(8)
	v_mfma_f32_16x16x32_bf16 v[136:139], v[92:95], v[48:51], v[22:25]
	v_mfma_f32_16x16x32_bf16 v[136:139], v[96:99], v[52:55], v[136:139]
	s_waitcnt lgkmcnt(6)
	v_mfma_f32_16x16x32_bf16 v[140:143], v[100:103], v[48:51], v[22:25]
	v_mfma_f32_16x16x32_bf16 v[140:143], v[104:107], v[52:55], v[140:143]
	s_add_i32 s5, s91, 6
	s_and_b32 s5, s5, 31
	s_lshl_b32 s5, s5, 11
	v_add_u32_e32 v0, s5, v4
	v_add_u32_e32 v1, s5, v5
	ds_read_b128 v[84:87], v0
	ds_read_b128 v[88:91], v1
	s_add_i32 s5, s91, 7
	s_and_b32 s5, s5, 31
	s_lshl_b32 s5, s5, 11
	v_add_u32_e32 v0, s5, v4
	v_add_u32_e32 v1, s5, v5
	ds_read_b128 v[92:95], v0
	ds_read_b128 v[96:99], v1
	s_add_i32 s5, s91, 8
	s_and_b32 s5, s5, 31
	s_lshl_b32 s5, s5, 11
	v_add_u32_e32 v0, s5, v4
	v_add_u32_e32 v1, s5, v5
	ds_read_b128 v[100:103], v0
	ds_read_b128 v[104:107], v1
	s_waitcnt lgkmcnt(10)
	v_mfma_f32_16x16x32_bf16 v[144:147], v[108:111], v[48:51], v[22:25]
	v_mfma_f32_16x16x32_bf16 v[144:147], v[112:115], v[52:55], v[144:147]
	s_waitcnt lgkmcnt(8)
	v_mfma_f32_16x16x32_bf16 v[148:151], v[116:119], v[48:51], v[22:25]
	v_mfma_f32_16x16x32_bf16 v[148:151], v[120:123], v[52:55], v[148:151]
	s_waitcnt lgkmcnt(6)
	v_mfma_f32_16x16x32_bf16 v[152:155], v[124:127], v[48:51], v[22:25]
	v_mfma_f32_16x16x32_bf16 v[152:155], v[128:131], v[52:55], v[152:155]
	s_waitcnt lgkmcnt(4)
	v_mfma_f32_16x16x32_bf16 v[160:163], v[84:87], v[48:51], v[22:25]
	v_mfma_f32_16x16x32_bf16 v[160:163], v[88:91], v[52:55], v[160:163]
	s_waitcnt lgkmcnt(2)
	v_mfma_f32_16x16x32_bf16 v[164:167], v[92:95], v[48:51], v[22:25]
	v_mfma_f32_16x16x32_bf16 v[164:167], v[96:99], v[52:55], v[164:167]
	s_waitcnt lgkmcnt(0)
	v_mfma_f32_16x16x32_bf16 v[168:171], v[100:103], v[48:51], v[22:25]
	v_mfma_f32_16x16x32_bf16 v[168:171], v[104:107], v[52:55], v[168:171]
	s_nop 7
	s_nop 3
	v_cndmask_b32_e64 v132, v132, v223, s[54:55]
	v_cndmask_b32_e64 v133, v133, v223, s[56:57]
	v_cndmask_b32_e64 v134, v134, v223, s[58:59]
	v_cndmask_b32_e64 v135, v135, v223, s[60:61]
	v_cndmask_b32_e64 v168, v168, v223, s[70:71]
	v_cndmask_b32_e64 v169, v169, v223, s[72:73]
	v_cndmask_b32_e64 v170, v170, v223, s[74:75]
	v_cndmask_b32_e64 v171, v171, v223, s[76:77]
	v_max3_f32 v0, v132, v133, v134
	v_max_f32_e32 v0, v0, v135
	v_add_f32_e32 v35, v0, v26
	v_max3_f32 v0, v136, v137, v138
	v_max_f32_e32 v0, v0, v139
	v_add_f32_e32 v0, v0, v27
	v_max_f32_e32 v35, v35, v0
	v_max3_f32 v0, v140, v141, v142
	v_max_f32_e32 v0, v0, v143
	v_add_f32_e32 v0, v0, v28
	v_max_f32_e32 v35, v35, v0
	v_max3_f32 v0, v144, v145, v146
	v_max_f32_e32 v0, v0, v147
	v_add_f32_e32 v0, v0, v29
	v_max_f32_e32 v35, v35, v0
	v_max3_f32 v0, v148, v149, v150
	v_max_f32_e32 v0, v0, v151
	v_add_f32_e32 v0, v0, v30
	v_max_f32_e32 v35, v35, v0
	v_max3_f32 v0, v152, v153, v154
	v_max_f32_e32 v0, v0, v155
	v_add_f32_e32 v0, v0, v31
	v_max_f32_e32 v35, v35, v0
	v_max3_f32 v0, v160, v161, v162
	v_max_f32_e32 v0, v0, v163
	v_add_f32_e32 v0, v0, v32
	v_max_f32_e32 v35, v35, v0
	v_max3_f32 v0, v164, v165, v166
	v_max_f32_e32 v0, v0, v167
	v_add_f32_e32 v0, v0, v33
	v_max_f32_e32 v35, v35, v0
	v_max3_f32 v0, v168, v169, v170
	v_max_f32_e32 v0, v0, v171
	v_add_f32_e32 v0, v0, v34
	v_max_f32_e32 v35, v35, v0
	v_mov_b32_e32 v0, v35
	v_mov_b32_e32 v1, v35
	s_nop 1
	v_permlane16_swap_b32_e32 v0, v1
	s_nop 1
	v_max_f32_e32 v35, v0, v1
	v_mov_b32_e32 v0, v35
	v_mov_b32_e32 v1, v35
	s_nop 1
	v_permlane32_swap_b32_e32 v0, v1
	s_nop 1
	v_max_f32_e32 v35, v0, v1
	v_sub_f32_e32 v2, v26, v35
	v_add_f32_e32 v132, v132, v2
	v_add_f32_e32 v133, v133, v2
	v_add_f32_e32 v134, v134, v2
	v_add_f32_e32 v135, v135, v2
	v_exp_f32_e32 v132, v132
	v_exp_f32_e32 v133, v133
	v_exp_f32_e32 v134, v134
	v_exp_f32_e32 v135, v135
	v_add_f32_e32 v36, 0, v132
	v_add_f32_e32 v36, v133, v36
	v_add_f32_e32 v36, v134, v36
	v_add_f32_e32 v36, v135, v36
	v_cvt_pk_bf16_f32 v172, v132, v133
	v_cvt_pk_bf16_f32 v173, v134, v135
	v_sub_f32_e32 v2, v27, v35
	v_add_f32_e32 v136, v136, v2
	v_add_f32_e32 v137, v137, v2
	v_add_f32_e32 v138, v138, v2
	v_add_f32_e32 v139, v139, v2
	v_exp_f32_e32 v136, v136
	v_exp_f32_e32 v137, v137
	v_exp_f32_e32 v138, v138
	v_exp_f32_e32 v139, v139
	v_add_f32_e32 v36, v136, v36
	v_add_f32_e32 v36, v137, v36
	v_add_f32_e32 v36, v138, v36
	v_add_f32_e32 v36, v139, v36
	v_cvt_pk_bf16_f32 v174, v136, v137
	v_cvt_pk_bf16_f32 v175, v138, v139
	v_sub_f32_e32 v2, v28, v35
	v_add_f32_e32 v140, v140, v2
	v_add_f32_e32 v141, v141, v2
	v_add_f32_e32 v142, v142, v2
	v_add_f32_e32 v143, v143, v2
	v_exp_f32_e32 v140, v140
	v_exp_f32_e32 v141, v141
	v_exp_f32_e32 v142, v142
	v_exp_f32_e32 v143, v143
	v_add_f32_e32 v36, v140, v36
	v_add_f32_e32 v36, v141, v36
	v_add_f32_e32 v36, v142, v36
	v_add_f32_e32 v36, v143, v36
	v_cvt_pk_bf16_f32 v176, v140, v141
	v_cvt_pk_bf16_f32 v177, v142, v143
	v_sub_f32_e32 v2, v29, v35
	v_add_f32_e32 v144, v144, v2
	v_add_f32_e32 v145, v145, v2
	v_add_f32_e32 v146, v146, v2
	v_add_f32_e32 v147, v147, v2
	v_exp_f32_e32 v144, v144
	v_exp_f32_e32 v145, v145
	v_exp_f32_e32 v146, v146
	v_exp_f32_e32 v147, v147
	v_add_f32_e32 v36, v144, v36
	v_add_f32_e32 v36, v145, v36
	v_add_f32_e32 v36, v146, v36
	v_add_f32_e32 v36, v147, v36
	v_cvt_pk_bf16_f32 v178, v144, v145
	v_cvt_pk_bf16_f32 v179, v146, v147
	v_sub_f32_e32 v2, v30, v35
	v_add_f32_e32 v148, v148, v2
	v_add_f32_e32 v149, v149, v2
	v_add_f32_e32 v150, v150, v2
	v_add_f32_e32 v151, v151, v2
	v_exp_f32_e32 v148, v148
	v_exp_f32_e32 v149, v149
	v_exp_f32_e32 v150, v150
	v_exp_f32_e32 v151, v151
	v_add_f32_e32 v36, v148, v36
	v_add_f32_e32 v36, v149, v36
	v_add_f32_e32 v36, v150, v36
	v_add_f32_e32 v36, v151, v36
	v_cvt_pk_bf16_f32 v180, v148, v149
	v_cvt_pk_bf16_f32 v181, v150, v151
	v_sub_f32_e32 v2, v31, v35
	v_add_f32_e32 v152, v152, v2
	v_add_f32_e32 v153, v153, v2
	v_add_f32_e32 v154, v154, v2
	v_add_f32_e32 v155, v155, v2
	v_exp_f32_e32 v152, v152
	v_exp_f32_e32 v153, v153
	v_exp_f32_e32 v154, v154
	v_exp_f32_e32 v155, v155
	v_add_f32_e32 v36, v152, v36
	v_add_f32_e32 v36, v153, v36
	v_add_f32_e32 v36, v154, v36
	v_add_f32_e32 v36, v155, v36
	v_cvt_pk_bf16_f32 v182, v152, v153
	v_cvt_pk_bf16_f32 v183, v154, v155
	v_sub_f32_e32 v2, v32, v35
	v_add_f32_e32 v160, v160, v2
	v_add_f32_e32 v161, v161, v2
	v_add_f32_e32 v162, v162, v2
	v_add_f32_e32 v163, v163, v2
	v_exp_f32_e32 v160, v160
	v_exp_f32_e32 v161, v161
	v_exp_f32_e32 v162, v162
	v_exp_f32_e32 v163, v163
	v_add_f32_e32 v36, v160, v36
	v_add_f32_e32 v36, v161, v36
	v_add_f32_e32 v36, v162, v36
	v_add_f32_e32 v36, v163, v36
	v_cvt_pk_bf16_f32 v184, v160, v161
	v_cvt_pk_bf16_f32 v185, v162, v163
	v_sub_f32_e32 v2, v33, v35
	v_add_f32_e32 v164, v164, v2
	v_add_f32_e32 v165, v165, v2
	v_add_f32_e32 v166, v166, v2
	v_add_f32_e32 v167, v167, v2
	v_exp_f32_e32 v164, v164
	v_exp_f32_e32 v165, v165
	v_exp_f32_e32 v166, v166
	v_exp_f32_e32 v167, v167
	v_add_f32_e32 v36, v164, v36
	v_add_f32_e32 v36, v165, v36
	v_add_f32_e32 v36, v166, v36
	v_add_f32_e32 v36, v167, v36
	v_cvt_pk_bf16_f32 v186, v164, v165
	v_cvt_pk_bf16_f32 v187, v166, v167
	v_sub_f32_e32 v2, v34, v35
	v_add_f32_e32 v168, v168, v2
	v_add_f32_e32 v169, v169, v2
	v_add_f32_e32 v170, v170, v2
	v_add_f32_e32 v171, v171, v2
	v_exp_f32_e32 v168, v168
	v_exp_f32_e32 v169, v169
	v_exp_f32_e32 v170, v170
	v_exp_f32_e32 v171, v171
	v_add_f32_e32 v36, v168, v36
	v_add_f32_e32 v36, v169, v36
	v_add_f32_e32 v36, v170, v36
	v_add_f32_e32 v36, v171, v36
	v_cvt_pk_bf16_f32 v188, v168, v169
	v_cvt_pk_bf16_f32 v189, v170, v171
	v_mov_b32_e32 v2, 0
	s_cmp_eq_u32 s89, 1
	s_cbranch_scc1 .Latt_w14_20
	s_waitcnt vmcnt(16)
	s_branch .Latt_wj_21
.Latt_w14_20:
	s_waitcnt vmcnt(14)
.Latt_wj_21:
	s_waitcnt lgkmcnt(0)
	s_barrier
	s_add_i32 s4, s53, 1
	s_add_i32 s4, s4, s52
	s_min_u32 s4, s4, 47
	s_lshr_b32 s11, s4, 4
	s_and_b32 s12, s4, 15
	s_lshl_b32 s28, s11, 1
	s_lshl_b32 s13, s64, 4
	s_add_i32 s13, s13, s12
	s_lshr_b32 s14, s12, 2
	s_and_b32 s15, s12, 3
	s_lshl_b32 s16, s64, 2
	s_add_i32 s15, s16, s15
	s_cmp_eq_u32 s11, 1
	s_cselect_b32 s29, s14, 0
	s_cselect_b32 s30, s15, s13
	s_cmp_eq_u32 s11, 2
	s_cselect_b32 s29, s12, s29
	s_cselect_b32 s30, s64, s30
	s_lshr_b32 s11, s4, 4
	s_and_b32 s12, s4, 15
	s_and_b32 s13, s12, 3
	s_cmp_lg_u32 s12, 0
	s_cselect_b32 s14, 1, 0
	s_lshr_b32 s15, s12, 2
	s_and_b32 s16, s12, 3
	s_add_i32 s15, s15, s16
	s_add_i32 s15, s15, 1
	s_and_b32 s15, s15, 3
	s_cmp_lg_u32 s16, 0
	s_cselect_b32 s16, 1, 0
	s_cmp_eq_u32 s11, 1
	s_cselect_b32 s13, s15, s13
	s_cselect_b32 s14, s16, s14
	s_and_b32 s15, s12, 1
	s_lshl_b32 s15, s15, 1
	s_add_i32 s15, s15, 1
	s_cmp_eq_u32 s11, 2
	s_cselect_b32 s88, s15, s13
	s_cselect_b32 s89, 0, s14
	s_lshl_b32 s5, s88, 7
	s_lshl_b32 s6, s67, 3
	s_add_i32 s5, s5, s6
	s_add_i32 s6, s30, -1
	s_lshl_b32 s6, s6, 7
	s_cmp_eq_u32 s89, 1
	s_cbranch_scc1 .Latt_half_22
	s_add_i32 s7, s5, 0
	s_and_b32 s7, s7, 511
	s_lshl_b32 s7, s7, 7
	s_add_i32 m0, s7, s49
	s_add_i32 s7, s6, 0
	v_add_u32_e32 v0, s7, v14
	v_lshlrev_b32_e32 v0, s28, v0
	v_add_u32_e32 v0, s29, v0
	v_max_i32_e32 v0, 0, v0
	v_lshl_or_b32 v2, v0, 7, v15
	v_lshl_add_u64 v[38:39], s[50:51], 0, v[2:3]
	global_load_lds_dwordx4 v[38:39], off
	s_add_i32 s7, s5, 64
	s_and_b32 s7, s7, 511
	s_lshl_b32 s7, s7, 7
	s_add_i32 m0, s7, s49
	s_add_i32 s7, s6, 64
	v_add_u32_e32 v0, s7, v14
	v_lshlrev_b32_e32 v0, s28, v0
	v_add_u32_e32 v0, s29, v0
	v_max_i32_e32 v0, 0, v0
	v_lshl_or_b32 v2, v0, 7, v15
	v_lshl_add_u64 v[40:41], s[50:51], 0, v[2:3]
	global_load_lds_dwordx4 v[40:41], off
.Latt_half_22:
	s_add_i32 s7, s5, 128
	s_and_b32 s7, s7, 511
	s_lshl_b32 s7, s7, 7
	s_add_i32 m0, s7, s49
	s_add_i32 s7, s6, 128
	v_add_u32_e32 v0, s7, v14
	v_lshlrev_b32_e32 v0, s28, v0
	v_add_u32_e32 v0, s29, v0
	v_max_i32_e32 v0, 0, v0
	v_lshl_or_b32 v2, v0, 7, v15
	v_lshl_add_u64 v[42:43], s[50:51], 0, v[2:3]
	global_load_lds_dwordx4 v[42:43], off
	s_add_i32 s7, s5, 192
	s_and_b32 s7, s7, 511
	s_lshl_b32 s7, s7, 7
	s_add_i32 m0, s7, s49
	s_add_i32 s7, s6, 192
	v_add_u32_e32 v0, s7, v14
	v_lshlrev_b32_e32 v0, s28, v0
	v_add_u32_e32 v0, s29, v0
	v_max_i32_e32 v0, 0, v0
	v_lshl_or_b32 v2, v0, 7, v15
	v_lshl_add_u64 v[44:45], s[50:51], 0, v[2:3]
	global_load_lds_dwordx4 v[44:45], off
	s_add_i32 s4, s53, 2
	s_min_u32 s4, s4, 47
	s_lshr_b32 s11, s4, 4
	s_and_b32 s12, s4, 15
	s_lshl_b32 s8, s11, 1
	s_lshl_b32 s13, s64, 4
	s_add_i32 s13, s13, s12
	s_lshr_b32 s14, s12, 2
	s_and_b32 s15, s12, 3
	s_lshl_b32 s16, s64, 2
	s_add_i32 s15, s16, s15
	s_cmp_eq_u32 s11, 1
	s_cselect_b32 s17, s14, 0
	s_cselect_b32 s10, s15, s13
	s_cmp_eq_u32 s11, 2
	s_cselect_b32 s17, s12, s17
	s_cselect_b32 s10, s64, s10
	s_lshl_b32 s5, s10, 7
	v_add_u32_e32 v82, s5, v17
	v_lshlrev_b32_e32 v82, s8, v82
	v_add_u32_e32 v82, s17, v82
	v_lshl_add_u32 v1, v82, 11, v18
	global_load_dwordx4 v[48:51], v1, s[40:41]
	global_load_dwordx4 v[52:55], v1, s[40:41] offset:64
	s_add_i32 s5, s91, 0
	s_and_b32 s5, s5, 31
	s_lshl_b32 s5, s5, 11
	v_add_u32_e32 v37, s5, v6
	v_add_u32_e32 v38, s5, v7
	v_add_u32_e32 v39, s5, v8
	v_add_u32_e32 v40, s5, v9
	ds_read_b64_tr_b16 v[84:85], v37
	ds_read_b64_tr_b16 v[88:89], v38
	ds_read_b64_tr_b16 v[92:93], v39
	ds_read_b64_tr_b16 v[96:97], v40
	s_add_i32 s5, s91, 1
	s_and_b32 s5, s5, 31
	s_lshl_b32 s5, s5, 11
	v_add_u32_e32 v37, s5, v6
	v_add_u32_e32 v38, s5, v7
	v_add_u32_e32 v39, s5, v8
	v_add_u32_e32 v40, s5, v9
	ds_read_b64_tr_b16 v[86:87], v37
	ds_read_b64_tr_b16 v[90:91], v38
	ds_read_b64_tr_b16 v[94:95], v39
	ds_read_b64_tr_b16 v[98:99], v40
	s_add_i32 s5, s91, 2
	s_and_b32 s5, s5, 31
	s_lshl_b32 s5, s5, 11
	v_add_u32_e32 v37, s5, v6
	v_add_u32_e32 v38, s5, v7
	v_add_u32_e32 v39, s5, v8
	v_add_u32_e32 v40, s5, v9
	ds_read_b64_tr_b16 v[100:101], v37
	ds_read_b64_tr_b16 v[104:105], v38
	ds_read_b64_tr_b16 v[108:109], v39
	ds_read_b64_tr_b16 v[112:113], v40
	s_add_i32 s5, s91, 3
	s_and_b32 s5, s5, 31
	s_lshl_b32 s5, s5, 11
	v_add_u32_e32 v37, s5, v6
	v_add_u32_e32 v38, s5, v7
	v_add_u32_e32 v39, s5, v8
	v_add_u32_e32 v40, s5, v9
	ds_read_b64_tr_b16 v[102:103], v37
	ds_read_b64_tr_b16 v[106:107], v38
	ds_read_b64_tr_b16 v[110:111], v39
	ds_read_b64_tr_b16 v[114:115], v40
	s_waitcnt lgkmcnt(8)
	v_mfma_f32_16x16x32_bf16 v[228:231], v[84:87], v[172:175], 0
	v_mfma_f32_16x16x32_bf16 v[232:235], v[88:91], v[172:175], 0
	v_mfma_f32_16x16x32_bf16 v[236:239], v[92:95], v[172:175], 0
	v_mfma_f32_16x16x32_bf16 v[240:243], v[96:99], v[172:175], 0
	s_add_i32 s5, s91, 4
	s_and_b32 s5, s5, 31
	s_lshl_b32 s5, s5, 11
	v_add_u32_e32 v37, s5, v6
	v_add_u32_e32 v38, s5, v7
	v_add_u32_e32 v39, s5, v8
	v_add_u32_e32 v40, s5, v9
	ds_read_b64_tr_b16 v[84:85], v37
	ds_read_b64_tr_b16 v[88:89], v38
	ds_read_b64_tr_b16 v[92:93], v39
	ds_read_b64_tr_b16 v[96:97], v40
	s_add_i32 s5, s91, 5
	s_and_b32 s5, s5, 31
	s_lshl_b32 s5, s5, 11
	v_add_u32_e32 v37, s5, v6
	v_add_u32_e32 v38, s5, v7
	v_add_u32_e32 v39, s5, v8
	v_add_u32_e32 v40, s5, v9
	ds_read_b64_tr_b16 v[86:87], v37
	ds_read_b64_tr_b16 v[90:91], v38
	ds_read_b64_tr_b16 v[94:95], v39
	ds_read_b64_tr_b16 v[98:99], v40
	s_waitcnt lgkmcnt(8)
	v_mfma_f32_16x16x32_bf16 v[228:231], v[100:103], v[176:179], v[228:231]
	v_mfma_f32_16x16x32_bf16 v[232:235], v[104:107], v[176:179], v[232:235]
	v_mfma_f32_16x16x32_bf16 v[236:239], v[108:111], v[176:179], v[236:239]
	v_mfma_f32_16x16x32_bf16 v[240:243], v[112:115], v[176:179], v[240:243]
	s_add_i32 s5, s91, 6
	s_and_b32 s5, s5, 31
	s_lshl_b32 s5, s5, 11
	v_add_u32_e32 v37, s5, v6
	v_add_u32_e32 v38, s5, v7
	v_add_u32_e32 v39, s5, v8
	v_add_u32_e32 v40, s5, v9
	ds_read_b64_tr_b16 v[100:101], v37
	ds_read_b64_tr_b16 v[104:105], v38
	ds_read_b64_tr_b16 v[108:109], v39
	ds_read_b64_tr_b16 v[112:113], v40
	s_add_i32 s5, s91, 7
	s_and_b32 s5, s5, 31
	s_lshl_b32 s5, s5, 11
	v_add_u32_e32 v37, s5, v6
	v_add_u32_e32 v38, s5, v7
	v_add_u32_e32 v39, s5, v8
	v_add_u32_e32 v40, s5, v9
	ds_read_b64_tr_b16 v[102:103], v37
	ds_read_b64_tr_b16 v[106:107], v38
	ds_read_b64_tr_b16 v[110:111], v39
	ds_read_b64_tr_b16 v[114:115], v40
	s_waitcnt lgkmcnt(8)
	v_mfma_f32_16x16x32_bf16 v[228:231], v[84:87], v[180:183], v[228:231]
	v_mfma_f32_16x16x32_bf16 v[232:235], v[88:91], v[180:183], v[232:235]
	v_mfma_f32_16x16x32_bf16 v[236:239], v[92:95], v[180:183], v[236:239]
	v_mfma_f32_16x16x32_bf16 v[240:243], v[96:99], v[180:183], v[240:243]
	s_add_i32 s5, s91, 8
	s_and_b32 s5, s5, 31
	s_lshl_b32 s5, s5, 11
	v_add_u32_e32 v37, s5, v6
	v_add_u32_e32 v38, s5, v7
	v_add_u32_e32 v39, s5, v8
	v_add_u32_e32 v40, s5, v9
	ds_read_b64_tr_b16 v[84:85], v37
	ds_read_b64_tr_b16 v[88:89], v38
	ds_read_b64_tr_b16 v[92:93], v39
	ds_read_b64_tr_b16 v[96:97], v40
	s_add_i32 s5, s67, 9
	s_min_u32 s5, s5, 15
	s_lshl_b32 s6, s90, 3
	s_add_i32 s5, s5, s6
	s_and_b32 s5, s5, 31
	s_lshl_b32 s5, s5, 11
	v_add_u32_e32 v37, s5, v6
	v_add_u32_e32 v38, s5, v7
	v_add_u32_e32 v39, s5, v8
	v_add_u32_e32 v40, s5, v9
	ds_read_b64_tr_b16 v[86:87], v37
	ds_read_b64_tr_b16 v[90:91], v38
	ds_read_b64_tr_b16 v[94:95], v39
	ds_read_b64_tr_b16 v[98:99], v40
	s_waitcnt lgkmcnt(8)
	v_mfma_f32_16x16x32_bf16 v[228:231], v[100:103], v[184:187], v[228:231]
	v_mfma_f32_16x16x32_bf16 v[232:235], v[104:107], v[184:187], v[232:235]
	v_mfma_f32_16x16x32_bf16 v[236:239], v[108:111], v[184:187], v[236:239]
	v_mfma_f32_16x16x32_bf16 v[240:243], v[112:115], v[184:187], v[240:243]
	s_waitcnt lgkmcnt(0)
	v_mfma_f32_16x16x32_bf16 v[228:231], v[84:87], v[188:191], v[228:231]
	v_mfma_f32_16x16x32_bf16 v[232:235], v[88:91], v[188:191], v[232:235]
	v_mfma_f32_16x16x32_bf16 v[236:239], v[92:95], v[188:191], v[236:239]
	v_mfma_f32_16x16x32_bf16 v[240:243], v[96:99], v[188:191], v[240:243]
	v_mov_b32_e32 v0, v36
	v_mov_b32_e32 v1, v36
	s_nop 1
	v_permlane16_swap_b32_e32 v0, v1
	s_nop 1
	v_add_f32_e32 v36, v0, v1
	v_mov_b32_e32 v0, v36
	v_mov_b32_e32 v1, v36
	s_nop 1
	v_permlane32_swap_b32_e32 v0, v1
	s_nop 1
	v_add_f32_e32 v36, v0, v1
	s_cmp_lt_u32 s53, 16
	s_cbranch_scc0 .Latt_hasprev_23
	v_mov_b32_e32 v80, v223
	v_mov_b32_e32 v64, 0
	v_mov_b32_e32 v65, 0
	v_mov_b32_e32 v66, 0
	v_mov_b32_e32 v67, 0
	v_mov_b32_e32 v68, 0
	v_mov_b32_e32 v69, 0
	v_mov_b32_e32 v70, 0
	v_mov_b32_e32 v71, 0
.Latt_hasprev_23:
	v_max_f32_e32 v116, v80, v35
	v_sub_f32_e32 v117, v80, v116
	v_sub_f32_e32 v118, v35, v116
	v_exp_f32_e32 v117, v117
	v_exp_f32_e32 v118, v118
	s_lshl_b32 s5, s24, 7
	v_add_u32_e32 v83, s5, v17
	v_lshlrev_b32_e32 v83, s20, v83
	v_add_u32_e32 v83, s21, v83
	v_fma_f32 v119, v36, v118, v117
	v_rcp_f32_e32 v122, v119
	v_lshl_add_u32 v123, v83, 11, v19
	s_nop 0
	v_mul_f32_e32 v120, v117, v122
	v_mul_f32_e32 v121, v118, v122
	v_lshlrev_b32_e32 v124, 16, v64
	v_and_b32_e32 v125, 0xffff0000, v64
	v_lshlrev_b32_e32 v126, 16, v65
	v_and_b32_e32 v127, 0xffff0000, v65
	v_mul_f32_e32 v124, v120, v124
	v_mul_f32_e32 v125, v120, v125
	v_mul_f32_e32 v126, v120, v126
	v_mul_f32_e32 v127, v120, v127
	v_fma_f32 v124, v228, v121, v124
	v_fma_f32 v125, v229, v121, v125
	v_fma_f32 v126, v230, v121, v126
	v_fma_f32 v127, v231, v121, v127
	v_cvt_pk_bf16_f32 v128, v124, v125
	v_cvt_pk_bf16_f32 v129, v126, v127
	s_nop 0
	global_store_dwordx2 v123, v[128:129], s[42:43] offset:0
	v_lshlrev_b32_e32 v124, 16, v66
	v_and_b32_e32 v125, 0xffff0000, v66
	v_lshlrev_b32_e32 v126, 16, v67
	v_and_b32_e32 v127, 0xffff0000, v67
	v_mul_f32_e32 v124, v120, v124
	v_mul_f32_e32 v125, v120, v125
	v_mul_f32_e32 v126, v120, v126
	v_mul_f32_e32 v127, v120, v127
	v_fma_f32 v124, v232, v121, v124
	v_fma_f32 v125, v233, v121, v125
	v_fma_f32 v126, v234, v121, v126
	v_fma_f32 v127, v235, v121, v127
	v_cvt_pk_bf16_f32 v128, v124, v125
	v_cvt_pk_bf16_f32 v129, v126, v127
	s_nop 0
	global_store_dwordx2 v123, v[128:129], s[42:43] offset:32
	v_lshlrev_b32_e32 v124, 16, v68
	v_and_b32_e32 v125, 0xffff0000, v68
	v_lshlrev_b32_e32 v126, 16, v69
	v_and_b32_e32 v127, 0xffff0000, v69
	v_mul_f32_e32 v124, v120, v124
	v_mul_f32_e32 v125, v120, v125
	v_mul_f32_e32 v126, v120, v126
	v_mul_f32_e32 v127, v120, v127
	v_fma_f32 v124, v236, v121, v124
	v_fma_f32 v125, v237, v121, v125
	v_fma_f32 v126, v238, v121, v126
	v_fma_f32 v127, v239, v121, v127
	v_cvt_pk_bf16_f32 v128, v124, v125
	v_cvt_pk_bf16_f32 v129, v126, v127
	s_nop 0
	global_store_dwordx2 v123, v[128:129], s[42:43] offset:64
	v_lshlrev_b32_e32 v124, 16, v70
	v_and_b32_e32 v125, 0xffff0000, v70
	v_lshlrev_b32_e32 v126, 16, v71
	v_and_b32_e32 v127, 0xffff0000, v71
	v_mul_f32_e32 v124, v120, v124
	v_mul_f32_e32 v125, v120, v125
	v_mul_f32_e32 v126, v120, v126
	v_mul_f32_e32 v127, v120, v127
	v_fma_f32 v124, v240, v121, v124
	v_fma_f32 v125, v241, v121, v125
	v_fma_f32 v126, v242, v121, v126
	v_fma_f32 v127, v243, v121, v127
	v_cvt_pk_bf16_f32 v128, v124, v125
	v_cvt_pk_bf16_f32 v129, v126, v127
	s_nop 0
	global_store_dwordx2 v123, v[128:129], s[42:43] offset:96
	v_log_f32_e32 v130, v119
	v_lshlrev_b32_e32 v131, 2, v83
	s_nop 0
	v_add_f32_e32 v130, v116, v130
	s_mov_b64 exec, 0xffff
	global_store_dword v131, v130, s[44:45]
	s_mov_b64 exec, -1
	s_cmp_lt_u32 s4, 16
	s_cbranch_scc1 .Latt_odummy_24
	v_lshl_add_u32 v1, v82, 11, v19
	global_load_dwordx2 v[64:65], v1, s[42:43] offset:0
	global_load_dwordx2 v[66:67], v1, s[42:43] offset:32
	global_load_dwordx2 v[68:69], v1, s[42:43] offset:64
	global_load_dwordx2 v[70:71], v1, s[42:43] offset:96
	v_lshlrev_b32_e32 v0, 2, v82
	global_load_dword v80, v0, s[44:45]
	s_branch .Latt_odone_25

.Latt_odone_25:
	s_cmp_eq_u32 s89, 1
	s_cbranch_scc1 .Latt_w14_26
	s_waitcnt vmcnt(16)
	s_branch .Latt_wj_27

.Latt_wj_27:
	s_waitcnt lgkmcnt(0)
	s_barrier
	s_add_i32 s9, s53, 1
	s_lshr_b32 s11, s9, 4
	s_and_b32 s12, s9, 15
	s_lshl_b32 s20, s11, 1
	s_lshl_b32 s13, s64, 4
	s_add_i32 s13, s13, s12
	s_lshr_b32 s14, s12, 2
	s_and_b32 s15, s12, 3
	s_lshl_b32 s16, s64, 2
	s_add_i32 s15, s16, s15
	s_cmp_eq_u32 s11, 1
	s_cselect_b32 s21, s14, 0
	s_cselect_b32 s24, s15, s13
	s_cmp_eq_u32 s11, 2
	s_cselect_b32 s21, s12, s21
	s_cselect_b32 s24, s64, s24
	s_add_i32 s4, s9, 1
	s_min_u32 s4, s4, 47
	s_lshr_b32 s11, s4, 4
	s_and_b32 s12, s4, 15
	s_lshl_b32 s28, s11, 1
	s_lshl_b32 s13, s64, 4
	s_add_i32 s13, s13, s12
	s_lshr_b32 s14, s12, 2
	s_and_b32 s15, s12, 3
	s_lshl_b32 s16, s64, 2
	s_add_i32 s15, s16, s15
	s_cmp_eq_u32 s11, 1
	s_cselect_b32 s29, s14, 0
	s_cselect_b32 s30, s15, s13
	s_cmp_eq_u32 s11, 2
	s_cselect_b32 s29, s12, s29
	s_cselect_b32 s30, s64, s30
	s_lshr_b32 s11, s4, 4
	s_and_b32 s12, s4, 15
	s_and_b32 s13, s12, 3
	s_cmp_lg_u32 s12, 0
	s_cselect_b32 s14, 1, 0
	s_lshr_b32 s15, s12, 2
	s_and_b32 s16, s12, 3
	s_add_i32 s15, s15, s16
	s_add_i32 s15, s15, 1
	s_and_b32 s15, s15, 3
	s_cmp_lg_u32 s16, 0
	s_cselect_b32 s16, 1, 0
	s_cmp_eq_u32 s11, 1
	s_cselect_b32 s13, s15, s13
	s_cselect_b32 s14, s16, s14
	s_and_b32 s15, s12, 1
	s_lshl_b32 s15, s15, 1
	s_add_i32 s15, s15, 1
	s_cmp_eq_u32 s11, 2
	s_cselect_b32 s88, s15, s13
	s_cselect_b32 s89, 0, s14
	s_lshl_b32 s5, s88, 7
	s_lshl_b32 s6, s67, 3
	s_add_i32 s5, s5, s6
	s_add_i32 s6, s30, -1
	s_lshl_b32 s6, s6, 7
	s_cmp_eq_u32 s89, 1
	s_cbranch_scc1 .Latt_half_28
	s_add_i32 s7, s5, 0
	s_and_b32 s7, s7, 511
	s_lshl_b32 s7, s7, 7
	s_add_i32 m0, s7, s48
	s_add_i32 s7, s6, 0
	v_add_u32_e32 v0, s7, v14
	v_lshlrev_b32_e32 v0, s28, v0
	v_add_u32_e32 v0, s29, v0
	v_max_i32_e32 v0, 0, v0
	v_lshl_or_b32 v2, v0, 7, v15
	v_lshl_add_u64 v[38:39], s[46:47], 0, v[2:3]
	global_load_lds_dwordx4 v[38:39], off
	s_add_i32 s7, s5, 64
	s_and_b32 s7, s7, 511
	s_lshl_b32 s7, s7, 7
	s_add_i32 m0, s7, s48
	s_add_i32 s7, s6, 64
	v_add_u32_e32 v0, s7, v14
	v_lshlrev_b32_e32 v0, s28, v0
	v_add_u32_e32 v0, s29, v0
	v_max_i32_e32 v0, 0, v0
	v_lshl_or_b32 v2, v0, 7, v15
	v_lshl_add_u64 v[40:41], s[46:47], 0, v[2:3]
	global_load_lds_dwordx4 v[40:41], off
.Latt_half_28:
	s_add_i32 s7, s5, 128
	s_and_b32 s7, s7, 511
	s_lshl_b32 s7, s7, 7
	s_add_i32 m0, s7, s48
	s_add_i32 s7, s6, 128
	v_add_u32_e32 v0, s7, v14
	v_lshlrev_b32_e32 v0, s28, v0
	v_add_u32_e32 v0, s29, v0
	v_max_i32_e32 v0, 0, v0
	v_lshl_or_b32 v2, v0, 7, v15
	v_lshl_add_u64 v[42:43], s[46:47], 0, v[2:3]
	global_load_lds_dwordx4 v[42:43], off
	s_add_i32 s7, s5, 192
	s_and_b32 s7, s7, 511
	s_lshl_b32 s7, s7, 7
	s_add_i32 m0, s7, s48
	s_add_i32 s7, s6, 192
	v_add_u32_e32 v0, s7, v14
	v_lshlrev_b32_e32 v0, s28, v0
	v_add_u32_e32 v0, s29, v0
	v_max_i32_e32 v0, 0, v0
	v_lshl_or_b32 v2, v0, 7, v15
	v_lshl_add_u64 v[44:45], s[46:47], 0, v[2:3]
	global_load_lds_dwordx4 v[44:45], off
	s_lshr_b32 s11, s9, 4
	s_and_b32 s12, s9, 15
	s_and_b32 s13, s12, 3
	s_cmp_lg_u32 s12, 0
	s_cselect_b32 s14, 1, 0
	s_lshr_b32 s15, s12, 2
	s_and_b32 s16, s12, 3
	s_add_i32 s15, s15, s16
	s_add_i32 s15, s15, 1
	s_and_b32 s15, s15, 3
	s_cmp_lg_u32 s16, 0
	s_cselect_b32 s16, 1, 0
	s_cmp_eq_u32 s11, 1
	s_cselect_b32 s13, s15, s13
	s_cselect_b32 s14, s16, s14
	s_and_b32 s15, s12, 1
	s_lshl_b32 s15, s15, 1
	s_add_i32 s15, s15, 1
	s_cmp_eq_u32 s11, 2
	s_cselect_b32 s90, s15, s13
	s_cselect_b32 s31, 0, s14
	s_lshl_b32 s91, s90, 3
	s_add_i32 s91, s91, s67
	s_add_i32 s5, s91, 0
	s_and_b32 s5, s5, 31
	s_lshl_b32 s5, s5, 11
	v_add_u32_e32 v0, s5, v4
	v_add_u32_e32 v1, s5, v5
	ds_read_b128 v[84:87], v0
	ds_read_b128 v[88:91], v1
	s_add_i32 s5, s91, 1
	s_and_b32 s5, s5, 31
	s_lshl_b32 s5, s5, 11
	v_add_u32_e32 v0, s5, v4
	v_add_u32_e32 v1, s5, v5
	ds_read_b128 v[92:95], v0
	ds_read_b128 v[96:99], v1
	s_add_i32 s5, s91, 2
	s_and_b32 s5, s5, 31
	s_lshl_b32 s5, s5, 11
	v_add_u32_e32 v0, s5, v4
	v_add_u32_e32 v1, s5, v5
	ds_read_b128 v[100:103], v0
	ds_read_b128 v[104:107], v1
	s_add_i32 s5, s91, 3
	s_and_b32 s5, s5, 31
	s_lshl_b32 s5, s5, 11
	v_add_u32_e32 v0, s5, v4
	v_add_u32_e32 v1, s5, v5
	ds_read_b128 v[108:111], v0
	ds_read_b128 v[112:115], v1
	s_add_i32 s5, s91, 4
	s_and_b32 s5, s5, 31
	s_lshl_b32 s5, s5, 11
	v_add_u32_e32 v0, s5, v4
	v_add_u32_e32 v1, s5, v5
	ds_read_b128 v[116:119], v0
	ds_read_b128 v[120:123], v1
	s_add_i32 s5, s91, 5
	s_and_b32 s5, s5, 31
	s_lshl_b32 s5, s5, 11
	v_add_u32_e32 v0, s5, v4
	v_add_u32_e32 v1, s5, v5
	ds_read_b128 v[124:127], v0
	ds_read_b128 v[128:131], v1
	s_lshl_b32 s5, 1, s20
	v_cvt_f32_u32_e32 v0, s5
	v_mul_f32_e32 v21, v20, v0
	v_xor_b32_e32 v0, 0x80000000, v21
	v_mul_f32_e32 v22, v16, v0
	v_add_f32_e32 v23, v21, v22
	v_add_f32_e32 v1, v21, v21
	v_add_f32_e32 v24, v1, v22
	v_fma_f32 v25, v21, v192, v22
	v_mul_f32_e32 v26, 0, v21
	v_mul_f32_e32 v27, 0x41800000, v21
	v_mul_f32_e32 v28, 0x42000000, v21
	v_mul_f32_e32 v29, 0x42400000, v21
	v_mul_f32_e32 v30, 0x42800000, v21
	v_mul_f32_e32 v31, 0x42a00000, v21
	v_mul_f32_e32 v32, 0x42c00000, v21
	v_mul_f32_e32 v33, 0x42e00000, v21
	v_mul_f32_e32 v34, 0x43000000, v21
	s_cmp_eq_u32 s24, 0
	s_cbranch_scc0 .Latt_n0skip_29
	s_cmp_lt_u32 s67, 1
	s_cbranch_scc0 .Latt_n0t_30
	v_mov_b32_e32 v33, v223

.Latt_n0t_37:
.Latt_n0skip_29:
	s_waitcnt lgkmcnt(10)
	v_mfma_f32_16x16x32_bf16 v[132:135], v[84:87], v[56:59], v[22:25]
	v_mfma_f32_16x16x32_bf16 v[132:135], v[88:91], v[60:63], v[132:135]
	s_waitcnt lgkmcnt(8)
	v_mfma_f32_16x16x32_bf16 v[136:139], v[92:95], v[56:59], v[22:25]
	v_mfma_f32_16x16x32_bf16 v[136:139], v[96:99], v[60:63], v[136:139]
	s_waitcnt lgkmcnt(6)
	v_mfma_f32_16x16x32_bf16 v[140:143], v[100:103], v[56:59], v[22:25]
	v_mfma_f32_16x16x32_bf16 v[140:143], v[104:107], v[60:63], v[140:143]
	s_add_i32 s5, s91, 6
	s_and_b32 s5, s5, 31
	s_lshl_b32 s5, s5, 11
	v_add_u32_e32 v0, s5, v4
	v_add_u32_e32 v1, s5, v5
	ds_read_b128 v[84:87], v0
	ds_read_b128 v[88:91], v1
	s_add_i32 s5, s91, 7
	s_and_b32 s5, s5, 31
	s_lshl_b32 s5, s5, 11
	v_add_u32_e32 v0, s5, v4
	v_add_u32_e32 v1, s5, v5
	ds_read_b128 v[92:95], v0
	ds_read_b128 v[96:99], v1
	s_add_i32 s5, s91, 8
	s_and_b32 s5, s5, 31
	s_lshl_b32 s5, s5, 11
	v_add_u32_e32 v0, s5, v4
	v_add_u32_e32 v1, s5, v5
	ds_read_b128 v[100:103], v0
	ds_read_b128 v[104:107], v1
	s_waitcnt lgkmcnt(10)
	v_mfma_f32_16x16x32_bf16 v[144:147], v[108:111], v[56:59], v[22:25]
	v_mfma_f32_16x16x32_bf16 v[144:147], v[112:115], v[60:63], v[144:147]
	s_waitcnt lgkmcnt(8)
	v_mfma_f32_16x16x32_bf16 v[148:151], v[116:119], v[56:59], v[22:25]
	v_mfma_f32_16x16x32_bf16 v[148:151], v[120:123], v[60:63], v[148:151]
	s_waitcnt lgkmcnt(6)
	v_mfma_f32_16x16x32_bf16 v[152:155], v[124:127], v[56:59], v[22:25]
	v_mfma_f32_16x16x32_bf16 v[152:155], v[128:131], v[60:63], v[152:155]
	s_waitcnt lgkmcnt(4)
	v_mfma_f32_16x16x32_bf16 v[160:163], v[84:87], v[56:59], v[22:25]
	v_mfma_f32_16x16x32_bf16 v[160:163], v[88:91], v[60:63], v[160:163]
	s_waitcnt lgkmcnt(2)
	v_mfma_f32_16x16x32_bf16 v[164:167], v[92:95], v[56:59], v[22:25]
	v_mfma_f32_16x16x32_bf16 v[164:167], v[96:99], v[60:63], v[164:167]
	s_waitcnt lgkmcnt(0)
	v_mfma_f32_16x16x32_bf16 v[168:171], v[100:103], v[56:59], v[22:25]
	v_mfma_f32_16x16x32_bf16 v[168:171], v[104:107], v[60:63], v[168:171]
	s_nop 7
	s_nop 3
	v_cndmask_b32_e64 v132, v132, v223, s[54:55]
	v_cndmask_b32_e64 v133, v133, v223, s[56:57]
	v_cndmask_b32_e64 v134, v134, v223, s[58:59]
	v_cndmask_b32_e64 v135, v135, v223, s[60:61]
	v_cndmask_b32_e64 v168, v168, v223, s[70:71]
	v_cndmask_b32_e64 v169, v169, v223, s[72:73]
	v_cndmask_b32_e64 v170, v170, v223, s[74:75]
	v_cndmask_b32_e64 v171, v171, v223, s[76:77]
	v_max3_f32 v0, v132, v133, v134
	v_max_f32_e32 v0, v0, v135
	v_add_f32_e32 v35, v0, v26
	v_max3_f32 v0, v136, v137, v138
	v_max_f32_e32 v0, v0, v139
	v_add_f32_e32 v0, v0, v27
	v_max_f32_e32 v35, v35, v0
	v_max3_f32 v0, v140, v141, v142
	v_max_f32_e32 v0, v0, v143
	v_add_f32_e32 v0, v0, v28
	v_max_f32_e32 v35, v35, v0
	v_max3_f32 v0, v144, v145, v146
	v_max_f32_e32 v0, v0, v147
	v_add_f32_e32 v0, v0, v29
	v_max_f32_e32 v35, v35, v0
	v_max3_f32 v0, v148, v149, v150
	v_max_f32_e32 v0, v0, v151
	v_add_f32_e32 v0, v0, v30
	v_max_f32_e32 v35, v35, v0
	v_max3_f32 v0, v152, v153, v154
	v_max_f32_e32 v0, v0, v155
	v_add_f32_e32 v0, v0, v31
	v_max_f32_e32 v35, v35, v0
	v_max3_f32 v0, v160, v161, v162
	v_max_f32_e32 v0, v0, v163
	v_add_f32_e32 v0, v0, v32
	v_max_f32_e32 v35, v35, v0
	v_max3_f32 v0, v164, v165, v166
	v_max_f32_e32 v0, v0, v167
	v_add_f32_e32 v0, v0, v33
	v_max_f32_e32 v35, v35, v0
	v_max3_f32 v0, v168, v169, v170
	v_max_f32_e32 v0, v0, v171
	v_add_f32_e32 v0, v0, v34
	v_max_f32_e32 v35, v35, v0
	v_mov_b32_e32 v0, v35
	v_mov_b32_e32 v1, v35
	s_nop 1
	v_permlane16_swap_b32_e32 v0, v1
	s_nop 1
	v_max_f32_e32 v35, v0, v1
	v_mov_b32_e32 v0, v35
	v_mov_b32_e32 v1, v35
	s_nop 1
	v_permlane32_swap_b32_e32 v0, v1
	s_nop 1
	v_max_f32_e32 v35, v0, v1
	v_sub_f32_e32 v2, v26, v35
	v_add_f32_e32 v132, v132, v2
	v_add_f32_e32 v133, v133, v2
	v_add_f32_e32 v134, v134, v2
	v_add_f32_e32 v135, v135, v2
	v_exp_f32_e32 v132, v132
	v_exp_f32_e32 v133, v133
	v_exp_f32_e32 v134, v134
	v_exp_f32_e32 v135, v135
	v_add_f32_e32 v36, 0, v132
	v_add_f32_e32 v36, v133, v36
	v_add_f32_e32 v36, v134, v36
	v_add_f32_e32 v36, v135, v36
	v_cvt_pk_bf16_f32 v172, v132, v133
	v_cvt_pk_bf16_f32 v173, v134, v135
	v_sub_f32_e32 v2, v27, v35
	v_add_f32_e32 v136, v136, v2
	v_add_f32_e32 v137, v137, v2
	v_add_f32_e32 v138, v138, v2
	v_add_f32_e32 v139, v139, v2
	v_exp_f32_e32 v136, v136
	v_exp_f32_e32 v137, v137
	v_exp_f32_e32 v138, v138
	v_exp_f32_e32 v139, v139
	v_add_f32_e32 v36, v136, v36
	v_add_f32_e32 v36, v137, v36
	v_add_f32_e32 v36, v138, v36
	v_add_f32_e32 v36, v139, v36
	v_cvt_pk_bf16_f32 v174, v136, v137
	v_cvt_pk_bf16_f32 v175, v138, v139
	v_sub_f32_e32 v2, v28, v35
	v_add_f32_e32 v140, v140, v2
	v_add_f32_e32 v141, v141, v2
	v_add_f32_e32 v142, v142, v2
	v_add_f32_e32 v143, v143, v2
	v_exp_f32_e32 v140, v140
	v_exp_f32_e32 v141, v141
	v_exp_f32_e32 v142, v142
	v_exp_f32_e32 v143, v143
	v_add_f32_e32 v36, v140, v36
	v_add_f32_e32 v36, v141, v36
	v_add_f32_e32 v36, v142, v36
	v_add_f32_e32 v36, v143, v36
	v_cvt_pk_bf16_f32 v176, v140, v141
	v_cvt_pk_bf16_f32 v177, v142, v143
	v_sub_f32_e32 v2, v29, v35
	v_add_f32_e32 v144, v144, v2
	v_add_f32_e32 v145, v145, v2
	v_add_f32_e32 v146, v146, v2
	v_add_f32_e32 v147, v147, v2
	v_exp_f32_e32 v144, v144
	v_exp_f32_e32 v145, v145
	v_exp_f32_e32 v146, v146
	v_exp_f32_e32 v147, v147
	v_add_f32_e32 v36, v144, v36
	v_add_f32_e32 v36, v145, v36
	v_add_f32_e32 v36, v146, v36
	v_add_f32_e32 v36, v147, v36
	v_cvt_pk_bf16_f32 v178, v144, v145
	v_cvt_pk_bf16_f32 v179, v146, v147
	v_sub_f32_e32 v2, v30, v35
	v_add_f32_e32 v148, v148, v2
	v_add_f32_e32 v149, v149, v2
	v_add_f32_e32 v150, v150, v2
	v_add_f32_e32 v151, v151, v2
	v_exp_f32_e32 v148, v148
	v_exp_f32_e32 v149, v149
	v_exp_f32_e32 v150, v150
	v_exp_f32_e32 v151, v151
	v_add_f32_e32 v36, v148, v36
	v_add_f32_e32 v36, v149, v36
	v_add_f32_e32 v36, v150, v36
	v_add_f32_e32 v36, v151, v36
	v_cvt_pk_bf16_f32 v180, v148, v149
	v_cvt_pk_bf16_f32 v181, v150, v151
	v_sub_f32_e32 v2, v31, v35
	v_add_f32_e32 v152, v152, v2
	v_add_f32_e32 v153, v153, v2
	v_add_f32_e32 v154, v154, v2
	v_add_f32_e32 v155, v155, v2
	v_exp_f32_e32 v152, v152
	v_exp_f32_e32 v153, v153
	v_exp_f32_e32 v154, v154
	v_exp_f32_e32 v155, v155
	v_add_f32_e32 v36, v152, v36
	v_add_f32_e32 v36, v153, v36
	v_add_f32_e32 v36, v154, v36
	v_add_f32_e32 v36, v155, v36
	v_cvt_pk_bf16_f32 v182, v152, v153
	v_cvt_pk_bf16_f32 v183, v154, v155
	v_sub_f32_e32 v2, v32, v35
	v_add_f32_e32 v160, v160, v2
	v_add_f32_e32 v161, v161, v2
	v_add_f32_e32 v162, v162, v2
	v_add_f32_e32 v163, v163, v2
	v_exp_f32_e32 v160, v160
	v_exp_f32_e32 v161, v161
	v_exp_f32_e32 v162, v162
	v_exp_f32_e32 v163, v163
	v_add_f32_e32 v36, v160, v36
	v_add_f32_e32 v36, v161, v36
	v_add_f32_e32 v36, v162, v36
	v_add_f32_e32 v36, v163, v36
	v_cvt_pk_bf16_f32 v184, v160, v161
	v_cvt_pk_bf16_f32 v185, v162, v163
	v_sub_f32_e32 v2, v33, v35
	v_add_f32_e32 v164, v164, v2
	v_add_f32_e32 v165, v165, v2
	v_add_f32_e32 v166, v166, v2
	v_add_f32_e32 v167, v167, v2
	v_exp_f32_e32 v164, v164
	v_exp_f32_e32 v165, v165
	v_exp_f32_e32 v166, v166
	v_exp_f32_e32 v167, v167
	v_add_f32_e32 v36, v164, v36
	v_add_f32_e32 v36, v165, v36
	v_add_f32_e32 v36, v166, v36
	v_add_f32_e32 v36, v167, v36
	v_cvt_pk_bf16_f32 v186, v164, v165
	v_cvt_pk_bf16_f32 v187, v166, v167
	v_sub_f32_e32 v2, v34, v35
	v_add_f32_e32 v168, v168, v2
	v_add_f32_e32 v169, v169, v2
	v_add_f32_e32 v170, v170, v2
	v_add_f32_e32 v171, v171, v2
	v_exp_f32_e32 v168, v168
	v_exp_f32_e32 v169, v169
	v_exp_f32_e32 v170, v170
	v_exp_f32_e32 v171, v171
	v_add_f32_e32 v36, v168, v36
	v_add_f32_e32 v36, v169, v36
	v_add_f32_e32 v36, v170, v36
	v_add_f32_e32 v36, v171, v36
	v_cvt_pk_bf16_f32 v188, v168, v169
	v_cvt_pk_bf16_f32 v189, v170, v171
	v_mov_b32_e32 v2, 0
	s_cmp_eq_u32 s89, 1
	s_cbranch_scc1 .Latt_w14_38
	s_waitcnt vmcnt(16)
	s_branch .Latt_wj_39

.Latt_wj_39:
	s_waitcnt lgkmcnt(0)
	s_barrier
	s_add_i32 s9, s53, 1
	s_add_i32 s4, s9, 1
	s_add_i32 s4, s4, s52
	s_min_u32 s4, s4, 47
	s_lshr_b32 s11, s4, 4
	s_and_b32 s12, s4, 15
	s_lshl_b32 s28, s11, 1
	s_lshl_b32 s13, s64, 4
	s_add_i32 s13, s13, s12
	s_lshr_b32 s14, s12, 2
	s_and_b32 s15, s12, 3
	s_lshl_b32 s16, s64, 2
	s_add_i32 s15, s16, s15
	s_cmp_eq_u32 s11, 1
	s_cselect_b32 s29, s14, 0
	s_cselect_b32 s30, s15, s13
	s_cmp_eq_u32 s11, 2
	s_cselect_b32 s29, s12, s29
	s_cselect_b32 s30, s64, s30
	s_lshr_b32 s11, s4, 4
	s_and_b32 s12, s4, 15
	s_and_b32 s13, s12, 3
	s_cmp_lg_u32 s12, 0
	s_cselect_b32 s14, 1, 0
	s_lshr_b32 s15, s12, 2
	s_and_b32 s16, s12, 3
	s_add_i32 s15, s15, s16
	s_add_i32 s15, s15, 1
	s_and_b32 s15, s15, 3
	s_cmp_lg_u32 s16, 0
	s_cselect_b32 s16, 1, 0
	s_cmp_eq_u32 s11, 1
	s_cselect_b32 s13, s15, s13
	s_cselect_b32 s14, s16, s14
	s_and_b32 s15, s12, 1
	s_lshl_b32 s15, s15, 1
	s_add_i32 s15, s15, 1
	s_cmp_eq_u32 s11, 2
	s_cselect_b32 s88, s15, s13
	s_cselect_b32 s89, 0, s14
	s_lshl_b32 s5, s88, 7
	s_lshl_b32 s6, s67, 3
	s_add_i32 s5, s5, s6
	s_add_i32 s6, s30, -1
	s_lshl_b32 s6, s6, 7
	s_cmp_eq_u32 s89, 1
	s_cbranch_scc1 .Latt_half_40
	s_add_i32 s7, s5, 0
	s_and_b32 s7, s7, 511
	s_lshl_b32 s7, s7, 7
	s_add_i32 m0, s7, s49
	s_add_i32 s7, s6, 0
	v_add_u32_e32 v0, s7, v14
	v_lshlrev_b32_e32 v0, s28, v0
	v_add_u32_e32 v0, s29, v0
	v_max_i32_e32 v0, 0, v0
	v_lshl_or_b32 v2, v0, 7, v15
	v_lshl_add_u64 v[38:39], s[50:51], 0, v[2:3]
	global_load_lds_dwordx4 v[38:39], off
	s_add_i32 s7, s5, 64
	s_and_b32 s7, s7, 511
	s_lshl_b32 s7, s7, 7
	s_add_i32 m0, s7, s49
	s_add_i32 s7, s6, 64
	v_add_u32_e32 v0, s7, v14
	v_lshlrev_b32_e32 v0, s28, v0
	v_add_u32_e32 v0, s29, v0
	v_max_i32_e32 v0, 0, v0
	v_lshl_or_b32 v2, v0, 7, v15
	v_lshl_add_u64 v[40:41], s[50:51], 0, v[2:3]
	global_load_lds_dwordx4 v[40:41], off
.Latt_half_40:
	s_add_i32 s7, s5, 128
	s_and_b32 s7, s7, 511
	s_lshl_b32 s7, s7, 7
	s_add_i32 m0, s7, s49
	s_add_i32 s7, s6, 128
	v_add_u32_e32 v0, s7, v14
	v_lshlrev_b32_e32 v0, s28, v0
	v_add_u32_e32 v0, s29, v0
	v_max_i32_e32 v0, 0, v0
	v_lshl_or_b32 v2, v0, 7, v15
	v_lshl_add_u64 v[42:43], s[50:51], 0, v[2:3]
	global_load_lds_dwordx4 v[42:43], off
	s_add_i32 s7, s5, 192
	s_and_b32 s7, s7, 511
	s_lshl_b32 s7, s7, 7
	s_add_i32 m0, s7, s49
	s_add_i32 s7, s6, 192
	v_add_u32_e32 v0, s7, v14
	v_lshlrev_b32_e32 v0, s28, v0
	v_add_u32_e32 v0, s29, v0
	v_max_i32_e32 v0, 0, v0
	v_lshl_or_b32 v2, v0, 7, v15
	v_lshl_add_u64 v[44:45], s[50:51], 0, v[2:3]
	global_load_lds_dwordx4 v[44:45], off
	s_add_i32 s4, s9, 2
	s_min_u32 s4, s4, 47
	s_lshr_b32 s11, s4, 4
	s_and_b32 s12, s4, 15
	s_lshl_b32 s8, s11, 1
	s_lshl_b32 s13, s64, 4
	s_add_i32 s13, s13, s12
	s_lshr_b32 s14, s12, 2
	s_and_b32 s15, s12, 3
	s_lshl_b32 s16, s64, 2
	s_add_i32 s15, s16, s15
	s_cmp_eq_u32 s11, 1
	s_cselect_b32 s17, s14, 0
	s_cselect_b32 s10, s15, s13
	s_cmp_eq_u32 s11, 2
	s_cselect_b32 s17, s12, s17
	s_cselect_b32 s10, s64, s10
	s_lshl_b32 s5, s10, 7
	v_add_u32_e32 v82, s5, v17
	v_lshlrev_b32_e32 v82, s8, v82
	v_add_u32_e32 v82, s17, v82
	v_lshl_add_u32 v1, v82, 11, v18
	global_load_dwordx4 v[56:59], v1, s[40:41]
	global_load_dwordx4 v[60:63], v1, s[40:41] offset:64
	s_add_i32 s5, s91, 0
	s_and_b32 s5, s5, 31
	s_lshl_b32 s5, s5, 11
	v_add_u32_e32 v37, s5, v6
	v_add_u32_e32 v38, s5, v7
	v_add_u32_e32 v39, s5, v8
	v_add_u32_e32 v40, s5, v9
	ds_read_b64_tr_b16 v[84:85], v37
	ds_read_b64_tr_b16 v[88:89], v38
	ds_read_b64_tr_b16 v[92:93], v39
	ds_read_b64_tr_b16 v[96:97], v40
	s_add_i32 s5, s91, 1
	s_and_b32 s5, s5, 31
	s_lshl_b32 s5, s5, 11
	v_add_u32_e32 v37, s5, v6
	v_add_u32_e32 v38, s5, v7
	v_add_u32_e32 v39, s5, v8
	v_add_u32_e32 v40, s5, v9
	ds_read_b64_tr_b16 v[86:87], v37
	ds_read_b64_tr_b16 v[90:91], v38
	ds_read_b64_tr_b16 v[94:95], v39
	ds_read_b64_tr_b16 v[98:99], v40
	s_add_i32 s5, s91, 2
	s_and_b32 s5, s5, 31
	s_lshl_b32 s5, s5, 11
	v_add_u32_e32 v37, s5, v6
	v_add_u32_e32 v38, s5, v7
	v_add_u32_e32 v39, s5, v8
	v_add_u32_e32 v40, s5, v9
	ds_read_b64_tr_b16 v[100:101], v37
	ds_read_b64_tr_b16 v[104:105], v38
	ds_read_b64_tr_b16 v[108:109], v39
	ds_read_b64_tr_b16 v[112:113], v40
	s_add_i32 s5, s91, 3
	s_and_b32 s5, s5, 31
	s_lshl_b32 s5, s5, 11
	v_add_u32_e32 v37, s5, v6
	v_add_u32_e32 v38, s5, v7
	v_add_u32_e32 v39, s5, v8
	v_add_u32_e32 v40, s5, v9
	ds_read_b64_tr_b16 v[102:103], v37
	ds_read_b64_tr_b16 v[106:107], v38
	ds_read_b64_tr_b16 v[110:111], v39
	ds_read_b64_tr_b16 v[114:115], v40
	s_waitcnt lgkmcnt(8)
	v_mfma_f32_16x16x32_bf16 v[228:231], v[84:87], v[172:175], 0
	v_mfma_f32_16x16x32_bf16 v[232:235], v[88:91], v[172:175], 0
	v_mfma_f32_16x16x32_bf16 v[236:239], v[92:95], v[172:175], 0
	v_mfma_f32_16x16x32_bf16 v[240:243], v[96:99], v[172:175], 0
	s_add_i32 s5, s91, 4
	s_and_b32 s5, s5, 31
	s_lshl_b32 s5, s5, 11
	v_add_u32_e32 v37, s5, v6
	v_add_u32_e32 v38, s5, v7
	v_add_u32_e32 v39, s5, v8
	v_add_u32_e32 v40, s5, v9
	ds_read_b64_tr_b16 v[84:85], v37
	ds_read_b64_tr_b16 v[88:89], v38
	ds_read_b64_tr_b16 v[92:93], v39
	ds_read_b64_tr_b16 v[96:97], v40
	s_add_i32 s5, s91, 5
	s_and_b32 s5, s5, 31
	s_lshl_b32 s5, s5, 11
	v_add_u32_e32 v37, s5, v6
	v_add_u32_e32 v38, s5, v7
	v_add_u32_e32 v39, s5, v8
	v_add_u32_e32 v40, s5, v9
	ds_read_b64_tr_b16 v[86:87], v37
	ds_read_b64_tr_b16 v[90:91], v38
	ds_read_b64_tr_b16 v[94:95], v39
	ds_read_b64_tr_b16 v[98:99], v40
	s_waitcnt lgkmcnt(8)
	v_mfma_f32_16x16x32_bf16 v[228:231], v[100:103], v[176:179], v[228:231]
	v_mfma_f32_16x16x32_bf16 v[232:235], v[104:107], v[176:179], v[232:235]
	v_mfma_f32_16x16x32_bf16 v[236:239], v[108:111], v[176:179], v[236:239]
	v_mfma_f32_16x16x32_bf16 v[240:243], v[112:115], v[176:179], v[240:243]
	s_add_i32 s5, s91, 6
	s_and_b32 s5, s5, 31
	s_lshl_b32 s5, s5, 11
	v_add_u32_e32 v37, s5, v6
	v_add_u32_e32 v38, s5, v7
	v_add_u32_e32 v39, s5, v8
	v_add_u32_e32 v40, s5, v9
	ds_read_b64_tr_b16 v[100:101], v37
	ds_read_b64_tr_b16 v[104:105], v38
	ds_read_b64_tr_b16 v[108:109], v39
	ds_read_b64_tr_b16 v[112:113], v40
	s_add_i32 s5, s91, 7
	s_and_b32 s5, s5, 31
	s_lshl_b32 s5, s5, 11
	v_add_u32_e32 v37, s5, v6
	v_add_u32_e32 v38, s5, v7
	v_add_u32_e32 v39, s5, v8
	v_add_u32_e32 v40, s5, v9
	ds_read_b64_tr_b16 v[102:103], v37
	ds_read_b64_tr_b16 v[106:107], v38
	ds_read_b64_tr_b16 v[110:111], v39
	ds_read_b64_tr_b16 v[114:115], v40
	s_waitcnt lgkmcnt(8)
	v_mfma_f32_16x16x32_bf16 v[228:231], v[84:87], v[180:183], v[228:231]
	v_mfma_f32_16x16x32_bf16 v[232:235], v[88:91], v[180:183], v[232:235]
	v_mfma_f32_16x16x32_bf16 v[236:239], v[92:95], v[180:183], v[236:239]
	v_mfma_f32_16x16x32_bf16 v[240:243], v[96:99], v[180:183], v[240:243]
	s_add_i32 s5, s91, 8
	s_and_b32 s5, s5, 31
	s_lshl_b32 s5, s5, 11
	v_add_u32_e32 v37, s5, v6
	v_add_u32_e32 v38, s5, v7
	v_add_u32_e32 v39, s5, v8
	v_add_u32_e32 v40, s5, v9
	ds_read_b64_tr_b16 v[84:85], v37
	ds_read_b64_tr_b16 v[88:89], v38
	ds_read_b64_tr_b16 v[92:93], v39
	ds_read_b64_tr_b16 v[96:97], v40
	s_add_i32 s5, s67, 9
	s_min_u32 s5, s5, 15
	s_lshl_b32 s6, s90, 3
	s_add_i32 s5, s5, s6
	s_and_b32 s5, s5, 31
	s_lshl_b32 s5, s5, 11
	v_add_u32_e32 v37, s5, v6
	v_add_u32_e32 v38, s5, v7
	v_add_u32_e32 v39, s5, v8
	v_add_u32_e32 v40, s5, v9
	ds_read_b64_tr_b16 v[86:87], v37
	ds_read_b64_tr_b16 v[90:91], v38
	ds_read_b64_tr_b16 v[94:95], v39
	ds_read_b64_tr_b16 v[98:99], v40
	s_waitcnt lgkmcnt(8)
	v_mfma_f32_16x16x32_bf16 v[228:231], v[100:103], v[184:187], v[228:231]
	v_mfma_f32_16x16x32_bf16 v[232:235], v[104:107], v[184:187], v[232:235]
	v_mfma_f32_16x16x32_bf16 v[236:239], v[108:111], v[184:187], v[236:239]
	v_mfma_f32_16x16x32_bf16 v[240:243], v[112:115], v[184:187], v[240:243]
	s_waitcnt lgkmcnt(0)
	v_mfma_f32_16x16x32_bf16 v[228:231], v[84:87], v[188:191], v[228:231]
	v_mfma_f32_16x16x32_bf16 v[232:235], v[88:91], v[188:191], v[232:235]
	v_mfma_f32_16x16x32_bf16 v[236:239], v[92:95], v[188:191], v[236:239]
	v_mfma_f32_16x16x32_bf16 v[240:243], v[96:99], v[188:191], v[240:243]
	v_mov_b32_e32 v0, v36
	v_mov_b32_e32 v1, v36
	s_nop 1
	v_permlane16_swap_b32_e32 v0, v1
	s_nop 1
	v_add_f32_e32 v36, v0, v1
	v_mov_b32_e32 v0, v36
	v_mov_b32_e32 v1, v36
	s_nop 1
	v_permlane32_swap_b32_e32 v0, v1
	s_nop 1
	v_add_f32_e32 v36, v0, v1
	s_cmp_lt_u32 s9, 16
	s_cbranch_scc0 .Latt_hasprev_41
	v_mov_b32_e32 v81, v223
	v_mov_b32_e32 v72, 0
	v_mov_b32_e32 v73, 0
	v_mov_b32_e32 v74, 0
	v_mov_b32_e32 v75, 0
	v_mov_b32_e32 v76, 0
	v_mov_b32_e32 v77, 0
	v_mov_b32_e32 v78, 0
	v_mov_b32_e32 v79, 0
.Latt_hasprev_41:
	v_max_f32_e32 v116, v81, v35
	v_sub_f32_e32 v117, v81, v116
	v_sub_f32_e32 v118, v35, v116
	v_exp_f32_e32 v117, v117
	v_exp_f32_e32 v118, v118
	s_lshl_b32 s5, s24, 7
	v_add_u32_e32 v83, s5, v17
	v_lshlrev_b32_e32 v83, s20, v83
	v_add_u32_e32 v83, s21, v83
	v_fma_f32 v119, v36, v118, v117
	v_rcp_f32_e32 v122, v119
	v_lshl_add_u32 v123, v83, 11, v19
	s_nop 0
	v_mul_f32_e32 v120, v117, v122
	v_mul_f32_e32 v121, v118, v122
	v_lshlrev_b32_e32 v124, 16, v72
	v_and_b32_e32 v125, 0xffff0000, v72
	v_lshlrev_b32_e32 v126, 16, v73
	v_and_b32_e32 v127, 0xffff0000, v73
	v_mul_f32_e32 v124, v120, v124
	v_mul_f32_e32 v125, v120, v125
	v_mul_f32_e32 v126, v120, v126
	v_mul_f32_e32 v127, v120, v127
	v_fma_f32 v124, v228, v121, v124
	v_fma_f32 v125, v229, v121, v125
	v_fma_f32 v126, v230, v121, v126
	v_fma_f32 v127, v231, v121, v127
	v_cvt_pk_bf16_f32 v128, v124, v125
	v_cvt_pk_bf16_f32 v129, v126, v127
	s_nop 0
	global_store_dwordx2 v123, v[128:129], s[42:43] offset:0
	v_lshlrev_b32_e32 v124, 16, v74
	v_and_b32_e32 v125, 0xffff0000, v74
	v_lshlrev_b32_e32 v126, 16, v75
	v_and_b32_e32 v127, 0xffff0000, v75
	v_mul_f32_e32 v124, v120, v124
	v_mul_f32_e32 v125, v120, v125
	v_mul_f32_e32 v126, v120, v126
	v_mul_f32_e32 v127, v120, v127
	v_fma_f32 v124, v232, v121, v124
	v_fma_f32 v125, v233, v121, v125
	v_fma_f32 v126, v234, v121, v126
	v_fma_f32 v127, v235, v121, v127
	v_cvt_pk_bf16_f32 v128, v124, v125
	v_cvt_pk_bf16_f32 v129, v126, v127
	s_nop 0
	global_store_dwordx2 v123, v[128:129], s[42:43] offset:32
	v_lshlrev_b32_e32 v124, 16, v76
	v_and_b32_e32 v125, 0xffff0000, v76
	v_lshlrev_b32_e32 v126, 16, v77
	v_and_b32_e32 v127, 0xffff0000, v77
	v_mul_f32_e32 v124, v120, v124
	v_mul_f32_e32 v125, v120, v125
	v_mul_f32_e32 v126, v120, v126
	v_mul_f32_e32 v127, v120, v127
	v_fma_f32 v124, v236, v121, v124
	v_fma_f32 v125, v237, v121, v125
	v_fma_f32 v126, v238, v121, v126
	v_fma_f32 v127, v239, v121, v127
	v_cvt_pk_bf16_f32 v128, v124, v125
	v_cvt_pk_bf16_f32 v129, v126, v127
	s_nop 0
	global_store_dwordx2 v123, v[128:129], s[42:43] offset:64
	v_lshlrev_b32_e32 v124, 16, v78
	v_and_b32_e32 v125, 0xffff0000, v78
	v_lshlrev_b32_e32 v126, 16, v79
	v_and_b32_e32 v127, 0xffff0000, v79
	v_mul_f32_e32 v124, v120, v124
	v_mul_f32_e32 v125, v120, v125
	v_mul_f32_e32 v126, v120, v126
	v_mul_f32_e32 v127, v120, v127
	v_fma_f32 v124, v240, v121, v124
	v_fma_f32 v125, v241, v121, v125
	v_fma_f32 v126, v242, v121, v126
	v_fma_f32 v127, v243, v121, v127
	v_cvt_pk_bf16_f32 v128, v124, v125
	v_cvt_pk_bf16_f32 v129, v126, v127
	s_nop 0
	global_store_dwordx2 v123, v[128:129], s[42:43] offset:96
	v_log_f32_e32 v130, v119
	v_lshlrev_b32_e32 v131, 2, v83
	s_nop 0
	v_add_f32_e32 v130, v116, v130
	s_mov_b64 exec, 0xffff
	global_store_dword v131, v130, s[44:45]
	s_mov_b64 exec, -1
	s_cmp_lt_u32 s4, 16
	s_cbranch_scc1 .Latt_odummy_42
	v_lshl_add_u32 v1, v82, 11, v19
	global_load_dwordx2 v[72:73], v1, s[42:43] offset:0
	global_load_dwordx2 v[74:75], v1, s[42:43] offset:32
	global_load_dwordx2 v[76:77], v1, s[42:43] offset:64
	global_load_dwordx2 v[78:79], v1, s[42:43] offset:96
	v_lshlrev_b32_e32 v0, 2, v82
	global_load_dword v81, v0, s[44:45]
	s_branch .Latt_odone_43

.Latt_wj_45:
	s_waitcnt lgkmcnt(0)
	s_barrier
	s_add_i32 s53, s53, 2
	s_cmp_lt_u32 s53, 48
	s_cbranch_scc1 .Latt_blk
	s_cmp_eq_u32 s68, 0
	s_cbranch_scc0 .Latt_tail_46
	s_barrier
